# plus: merged the back-to-back s_waitcnt vmcnt(8) / s_waitcnt lgkmcnt(0) pairs before the GEMM K-loop barriers into single waits
# speedup vs baseline: 1.0077x; 1.0038x over previous
; #define PG8_STAGE(bufoff, gbase, voff) do { _Pragma("unroll") for (int _i = 0; _i < 2; ++_i) \
;         __builtin_amdgcn_global_load_lds((const unsigned*)((const char*)(gbase) + (voff)[_i]), (PG8_LAS unsigned*)(lds + (bufoff) + ldsw + _i * 8192), 16, 0, 0); } while (0)
; #define PG8_LDA(dst, b, h) do { _Pragma("unroll") for (int m = 0; m < 4; ++m) _Pragma("unroll") for (int k = 0; k < 2; ++k) dst[m][k] = *(const PG8_LAS bf16x8*)(lds + PG8_SA(b, h) + aoff + m * 2048 + k * 1024); } while (0)
; #define PG8_LDB(dst, b, h) do { _Pragma("unroll") for (int n = 0; n < 2; ++n) _Pragma("unroll") for (int k = 0; k < 2; ++k) dst[n][k] = *(const PG8_LAS bf16x8*)(lds + PG8_SB(b, h) + boff + n * 2048 + k * 1024); } while (0)
; #define PG8_MMA(ai, bj, At, Bt) do { __builtin_amdgcn_s_setprio(1); _Pragma("unroll") for (int m = 0; m < 4; ++m) _Pragma("unroll") for (int n = 0; n < 2; ++n) _Pragma("unroll") for (int k = 0; k < 2; ++k) \
;         acc[ai][bj][m][n] = __builtin_amdgcn_mfma_f32_16x16x32_bf16(Bt[n][k], At[m][k], acc[ai][bj][m][n], 0, 0, 0); __builtin_amdgcn_s_setprio(0); } while (0)
; #define PG8_WAIT_V(n) asm volatile("s_waitcnt vmcnt(" #n ")" ::: "memory")
; #define PG8_WAIT_L(n) asm volatile("s_waitcnt lgkmcnt(" #n ")" ::: "memory")
; #define PG8_BAR __builtin_amdgcn_s_barrier()
; #define PG8_SCHED __builtin_amdgcn_sched_barrier(0)
; template <class Epi, class Sched, bool ALIGN_EPI = false, bool SP2 = false>
; __device__ __forceinline__ void gemm_phase(PG8_LAS unsigned char* lds, const Gemm g, const Sched& S, const Epi& E, const int tid) {
;     ...
;             const bool last = (t == nt - 2);
;             const char* a1 = cA + (size_t)(t + 1) * kstep;
;             const char* a2 = last ? nA : cA + (size_t)(t + 2) * kstep; const char* b2 = last ? nB : cB + (size_t)(t + 2) * kstep;
;             const char* a3 = a2 + kstep; const char* b3 = b2 + kstep;
;             if (last && has_next) S.a_ready(nxt);
;             if constexpr (SP2) {
;             PG8_LDB(B0, 0, 0); PG8_LDB(B1, 0, 1); PG8_SCHED; PG8_LDA(At, 0, 0); PG8_STAGE(PG8_SA(1, 1), a1 + hstepA, voffA);
;             PG8_WAIT_V(8); PG8_WAIT_L(0); PG8_BAR; PG8_MMA(0, 0, At, B0); PG8_MMA(0, 1, At, B1); PG8_BAR; PG8_SCHED;
;             PG8_LDA(At, 0, 1); PG8_STAGE(PG8_SB(0, 0), b2, voffB); PG8_STAGE(PG8_SB(0, 1), b2 + hstepB, voffB); PG8_STAGE(PG8_SA(0, 0), a2, voffA);
.LBB0_36:
	s_add_u32 s24, s46, 0xfffc0080
	s_addc_u32 s25, s47, -1
	s_add_i32 s63, 0, 0x10000
	s_cmp_eq_u32 s59, 12
	s_cselect_b32 s51, s19, s25
	s_cselect_b32 s50, s53, s24
	s_cselect_b32 s49, s15, s58
	s_cselect_b32 s48, s54, s55
	s_add_i32 s65, 0, 0x14000
	v_add_u32_e32 v154, s63, v143
	v_add_u32_e32 v170, s65, v143
	ds_read_b128 v[138:141], v154
	ds_read_b128 v[146:149], v154 offset:1024
	ds_read_b128 v[150:153], v154 offset:2048
	ds_read_b128 v[154:157], v154 offset:3072
	ds_read_b128 v[158:161], v170
	ds_read_b128 v[162:165], v170 offset:1024
	ds_read_b128 v[166:169], v170 offset:2048
	ds_read_b128 v[170:173], v170 offset:3072
	v_lshl_add_u64 v[190:191], s[46:47], 0, v[136:137]
	s_add_i32 m0, s23, 0xc000
	ds_read_b128 v[174:177], v145
	ds_read_b128 v[178:181], v145 offset:1024
	ds_read_b128 v[182:185], v145 offset:2048
	ds_read_b128 v[186:189], v145 offset:3072
	ds_read_b128 v[200:203], v145 offset:4096
	ds_read_b128 v[204:207], v145 offset:5120
	ds_read_b128 v[208:211], v145 offset:6144
	ds_read_b128 v[212:215], v145 offset:7168
	global_load_lds_dwordx4 v[190:191], off
	v_lshl_add_u64 v[190:191], s[46:47], 0, v[134:135]
	s_add_i32 m0, s23, 0xe000
	s_nop 0
	global_load_lds_dwordx4 v[190:191], off
	s_waitcnt vmcnt(8) lgkmcnt(0)
	s_barrier
	s_setprio 1
	v_mfma_f32_16x16x32_bf16 v[124:127], v[138:141], v[174:177], v[124:127]
	v_mfma_f32_16x16x32_bf16 v[120:123], v[150:153], v[174:177], v[120:123]
	v_mfma_f32_16x16x32_bf16 v[108:111], v[138:141], v[182:185], v[108:111]
	v_mfma_f32_16x16x32_bf16 v[104:107], v[150:153], v[182:185], v[104:107]
	v_mfma_f32_16x16x32_bf16 v[92:95], v[138:141], v[200:203], v[92:95]
	v_mfma_f32_16x16x32_bf16 v[88:91], v[150:153], v[200:203], v[88:91]
	v_mfma_f32_16x16x32_bf16 v[76:79], v[138:141], v[208:211], v[76:79]
	v_mfma_f32_16x16x32_bf16 v[72:75], v[150:153], v[208:211], v[72:75]
	v_mfma_f32_16x16x32_bf16 v[124:127], v[146:149], v[178:181], v[124:127]
	v_mfma_f32_16x16x32_bf16 v[120:123], v[154:157], v[178:181], v[120:123]
	v_mfma_f32_16x16x32_bf16 v[108:111], v[146:149], v[186:189], v[108:111]
	v_mfma_f32_16x16x32_bf16 v[104:107], v[154:157], v[186:189], v[104:107]
	v_mfma_f32_16x16x32_bf16 v[92:95], v[146:149], v[204:207], v[92:95]
	v_mfma_f32_16x16x32_bf16 v[88:91], v[154:157], v[204:207], v[88:91]
	v_mfma_f32_16x16x32_bf16 v[76:79], v[146:149], v[212:215], v[76:79]
	v_mfma_f32_16x16x32_bf16 v[72:75], v[154:157], v[212:215], v[72:75]
	s_setprio 0
	s_setprio 1
	v_mfma_f32_16x16x32_bf16 v[116:119], v[158:161], v[174:177], v[116:119]
	v_mfma_f32_16x16x32_bf16 v[112:115], v[166:169], v[174:177], v[112:115]
	v_mfma_f32_16x16x32_bf16 v[100:103], v[158:161], v[182:185], v[100:103]
	v_mfma_f32_16x16x32_bf16 v[96:99], v[166:169], v[182:185], v[96:99]
	v_mfma_f32_16x16x32_bf16 v[84:87], v[158:161], v[200:203], v[84:87]
	v_mfma_f32_16x16x32_bf16 v[80:83], v[166:169], v[200:203], v[80:83]
	v_mfma_f32_16x16x32_bf16 v[68:71], v[158:161], v[208:211], v[68:71]
	v_mfma_f32_16x16x32_bf16 v[64:67], v[166:169], v[208:211], v[64:67]
	v_mfma_f32_16x16x32_bf16 v[116:119], v[162:165], v[178:181], v[116:119]
	v_mfma_f32_16x16x32_bf16 v[112:115], v[170:173], v[178:181], v[112:115]
	v_mfma_f32_16x16x32_bf16 v[100:103], v[162:165], v[186:189], v[100:103]
	v_mfma_f32_16x16x32_bf16 v[96:99], v[170:173], v[186:189], v[96:99]
	v_mfma_f32_16x16x32_bf16 v[84:87], v[162:165], v[204:207], v[84:87]
	v_mfma_f32_16x16x32_bf16 v[80:83], v[170:173], v[204:207], v[80:83]
	v_mfma_f32_16x16x32_bf16 v[68:71], v[162:165], v[212:215], v[68:71]
	v_mfma_f32_16x16x32_bf16 v[64:67], v[170:173], v[212:215], v[64:67]
	s_setprio 0
	s_barrier
	s_add_i32 s24, s63, s21
	v_lshl_add_u64 v[190:191], s[48:49], 0, v[192:193]
	s_mov_b32 m0, s24
	ds_read_b128 v[174:177], v145 offset:16384
	ds_read_b128 v[178:181], v145 offset:17408
	ds_read_b128 v[182:185], v145 offset:18432
	ds_read_b128 v[186:189], v145 offset:19456
	ds_read_b128 v[200:203], v145 offset:20480
	ds_read_b128 v[204:207], v145 offset:21504
	ds_read_b128 v[208:211], v145 offset:22528
	ds_read_b128 v[212:215], v145 offset:23552
	global_load_lds_dwordx4 v[190:191], off
	s_add_i32 m0, s24, 0x2000
	s_add_u32 s24, s48, 0x40000
	v_lshl_add_u64 v[216:217], s[48:49], 0, v[128:129]
	s_addc_u32 s25, s49, 0
	s_add_i32 s63, s65, s21
	global_load_lds_dwordx4 v[216:217], off
	v_lshl_add_u64 v[218:219], s[24:25], 0, v[192:193]
	s_mov_b32 m0, s63
	v_lshl_add_u64 v[220:221], s[50:51], 0, v[130:131]
	global_load_lds_dwordx4 v[218:219], off
	v_lshl_add_u64 v[218:219], s[24:25], 0, v[128:129]
	s_add_i32 m0, s63, 0x2000
	s_nop 0
	global_load_lds_dwordx4 v[218:219], off
	v_lshl_add_u64 v[218:219], s[50:51], 0, v[132:133]
	s_mov_b32 m0, s23
	s_nop 0
	global_load_lds_dwordx4 v[218:219], off
	s_mov_b32 m0, s26
	s_nop 0
	global_load_lds_dwordx4 v[220:221], off
	s_waitcnt vmcnt(8) lgkmcnt(0)
	s_barrier
; #define PG8_STAGE(bufoff, gbase, voff) do { _Pragma("unroll") for (int _i = 0; _i < 2; ++_i) \
;         __builtin_amdgcn_global_load_lds((const unsigned*)((const char*)(gbase) + (voff)[_i]), (PG8_LAS unsigned*)(lds + (bufoff) + ldsw + _i * 8192), 16, 0, 0); } while (0)
; #define PG8_LDA(dst, b, h) do { _Pragma("unroll") for (int m = 0; m < 4; ++m) _Pragma("unroll") for (int k = 0; k < 2; ++k) dst[m][k] = *(const PG8_LAS bf16x8*)(lds + PG8_SA(b, h) + aoff + m * 2048 + k * 1024); } while (0)
; #define PG8_LDB(dst, b, h) do { _Pragma("unroll") for (int n = 0; n < 2; ++n) _Pragma("unroll") for (int k = 0; k < 2; ++k) dst[n][k] = *(const PG8_LAS bf16x8*)(lds + PG8_SB(b, h) + boff + n * 2048 + k * 1024); } while (0)
; #define PG8_MMA(ai, bj, At, Bt) do { __builtin_amdgcn_s_setprio(1); _Pragma("unroll") for (int m = 0; m < 4; ++m) _Pragma("unroll") for (int n = 0; n < 2; ++n) _Pragma("unroll") for (int k = 0; k < 2; ++k) \
;         acc[ai][bj][m][n] = __builtin_amdgcn_mfma_f32_16x16x32_bf16(Bt[n][k], At[m][k], acc[ai][bj][m][n], 0, 0, 0); __builtin_amdgcn_s_setprio(0); } while (0)
; #define PG8_WAIT_V(n) asm volatile("s_waitcnt vmcnt(" #n ")" ::: "memory")
; #define PG8_WAIT_L(n) asm volatile("s_waitcnt lgkmcnt(" #n ")" ::: "memory")
; #define PG8_BAR __builtin_amdgcn_s_barrier()
; #define PG8_SCHED __builtin_amdgcn_sched_barrier(0)
; template <class Epi, class Sched, bool ALIGN_EPI = false, bool SP2 = false>
; __device__ __forceinline__ void gemm_phase(PG8_LAS unsigned char* lds, const Gemm g, const Sched& S, const Epi& E, const int tid) {
;     ...
;             PG8_WAIT_V(8); PG8_WAIT_L(0); PG8_BAR; PG8_MMA(1, 0, At, B0); PG8_MMA(1, 1, At, B1); PG8_BAR; PG8_SCHED;
;             PG8_LDB(B0, 1, 0); PG8_LDB(B1, 1, 1); PG8_SCHED; PG8_LDA(At, 1, 0); PG8_STAGE(PG8_SA(0, 1), a2 + hstepA, voffA);
;             PG8_WAIT_V(8); PG8_WAIT_L(0); PG8_BAR; PG8_MMA(0, 0, At, B0); PG8_MMA(0, 1, At, B1); PG8_BAR; PG8_SCHED;
	s_setprio 1
	v_mfma_f32_16x16x32_bf16 v[60:63], v[138:141], v[174:177], v[60:63]
	v_mfma_f32_16x16x32_bf16 v[56:59], v[150:153], v[174:177], v[56:59]
	v_mfma_f32_16x16x32_bf16 v[44:47], v[138:141], v[182:185], v[44:47]
	v_mfma_f32_16x16x32_bf16 v[40:43], v[150:153], v[182:185], v[40:43]
	v_mfma_f32_16x16x32_bf16 v[28:31], v[138:141], v[200:203], v[28:31]
	v_mfma_f32_16x16x32_bf16 v[24:27], v[150:153], v[200:203], v[24:27]
	v_mfma_f32_16x16x32_bf16 v[12:15], v[138:141], v[208:211], v[12:15]
	v_mfma_f32_16x16x32_bf16 v[8:11], v[150:153], v[208:211], v[8:11]
	v_mfma_f32_16x16x32_bf16 v[60:63], v[146:149], v[178:181], v[60:63]
	v_mfma_f32_16x16x32_bf16 v[56:59], v[154:157], v[178:181], v[56:59]
	v_mfma_f32_16x16x32_bf16 v[44:47], v[146:149], v[186:189], v[44:47]
	v_mfma_f32_16x16x32_bf16 v[40:43], v[154:157], v[186:189], v[40:43]
	v_mfma_f32_16x16x32_bf16 v[28:31], v[146:149], v[204:207], v[28:31]
	v_mfma_f32_16x16x32_bf16 v[24:27], v[154:157], v[204:207], v[24:27]
	v_mfma_f32_16x16x32_bf16 v[12:15], v[146:149], v[212:215], v[12:15]
	v_mfma_f32_16x16x32_bf16 v[8:11], v[154:157], v[212:215], v[8:11]
	s_setprio 0
	s_setprio 1
	v_mfma_f32_16x16x32_bf16 v[52:55], v[158:161], v[174:177], v[52:55]
	v_mfma_f32_16x16x32_bf16 v[48:51], v[166:169], v[174:177], v[48:51]
	v_mfma_f32_16x16x32_bf16 v[36:39], v[158:161], v[182:185], v[36:39]
	v_mfma_f32_16x16x32_bf16 v[32:35], v[166:169], v[182:185], v[32:35]
	v_mfma_f32_16x16x32_bf16 v[20:23], v[158:161], v[200:203], v[20:23]
	v_mfma_f32_16x16x32_bf16 v[16:19], v[166:169], v[200:203], v[16:19]
	v_mfma_f32_16x16x32_bf16 v[4:7], v[158:161], v[208:211], v[4:7]
	v_mfma_f32_16x16x32_bf16 v[0:3], v[166:169], v[208:211], v[0:3]
	v_mfma_f32_16x16x32_bf16 v[52:55], v[162:165], v[178:181], v[52:55]
	v_mfma_f32_16x16x32_bf16 v[48:51], v[170:173], v[178:181], v[48:51]
	v_mfma_f32_16x16x32_bf16 v[36:39], v[162:165], v[186:189], v[36:39]
	v_mfma_f32_16x16x32_bf16 v[32:35], v[170:173], v[186:189], v[32:35]
	v_mfma_f32_16x16x32_bf16 v[20:23], v[162:165], v[204:207], v[20:23]
	v_mfma_f32_16x16x32_bf16 v[16:19], v[170:173], v[204:207], v[16:19]
	v_mfma_f32_16x16x32_bf16 v[4:7], v[162:165], v[212:215], v[4:7]
	v_mfma_f32_16x16x32_bf16 v[0:3], v[170:173], v[212:215], v[0:3]
	s_setprio 0
	s_barrier
	s_add_i32 s63, 0, 0x18000
	s_add_i32 s65, 0, 0x1c000
	v_add_u32_e32 v154, s63, v143
	v_add_u32_e32 v170, s65, v143
	ds_read_b128 v[138:141], v154
	ds_read_b128 v[146:149], v154 offset:1024
	ds_read_b128 v[150:153], v154 offset:2048
	ds_read_b128 v[154:157], v154 offset:3072
	ds_read_b128 v[158:161], v170
	ds_read_b128 v[162:165], v170 offset:1024
	ds_read_b128 v[166:169], v170 offset:2048
	ds_read_b128 v[170:173], v170 offset:3072
	s_add_u32 s24, s50, 0x40000
	s_addc_u32 s25, s51, 0
	s_mov_b32 m0, s27
	v_lshl_add_u64 v[222:223], s[24:25], 0, v[132:133]
	ds_read_b128 v[174:177], v145 offset:32768
	ds_read_b128 v[178:181], v145 offset:33792
	ds_read_b128 v[182:185], v145 offset:34816
	ds_read_b128 v[186:189], v145 offset:35840
	ds_read_b128 v[200:203], v145 offset:36864
	ds_read_b128 v[204:207], v145 offset:37888
	ds_read_b128 v[208:211], v145 offset:38912
	ds_read_b128 v[212:215], v145 offset:39936
	global_load_lds_dwordx4 v[222:223], off
	v_lshl_add_u64 v[222:223], s[24:25], 0, v[130:131]
	s_mov_b32 m0, s28
	s_nop 0
	global_load_lds_dwordx4 v[222:223], off
	s_waitcnt vmcnt(8) lgkmcnt(0)
	s_barrier
	s_setprio 1
	v_mfma_f32_16x16x32_bf16 v[124:127], v[138:141], v[174:177], v[124:127]
	v_mfma_f32_16x16x32_bf16 v[120:123], v[150:153], v[174:177], v[120:123]
	v_mfma_f32_16x16x32_bf16 v[108:111], v[138:141], v[182:185], v[108:111]
	v_mfma_f32_16x16x32_bf16 v[104:107], v[150:153], v[182:185], v[104:107]
	v_mfma_f32_16x16x32_bf16 v[92:95], v[138:141], v[200:203], v[92:95]
	v_mfma_f32_16x16x32_bf16 v[88:91], v[150:153], v[200:203], v[88:91]
	v_mfma_f32_16x16x32_bf16 v[76:79], v[138:141], v[208:211], v[76:79]
	v_mfma_f32_16x16x32_bf16 v[72:75], v[150:153], v[208:211], v[72:75]
	v_mfma_f32_16x16x32_bf16 v[124:127], v[146:149], v[178:181], v[124:127]
	v_mfma_f32_16x16x32_bf16 v[120:123], v[154:157], v[178:181], v[120:123]
	v_mfma_f32_16x16x32_bf16 v[108:111], v[146:149], v[186:189], v[108:111]
	v_mfma_f32_16x16x32_bf16 v[104:107], v[154:157], v[186:189], v[104:107]
	v_mfma_f32_16x16x32_bf16 v[92:95], v[146:149], v[204:207], v[92:95]
	v_mfma_f32_16x16x32_bf16 v[88:91], v[154:157], v[204:207], v[88:91]
	v_mfma_f32_16x16x32_bf16 v[76:79], v[146:149], v[212:215], v[76:79]
	v_mfma_f32_16x16x32_bf16 v[72:75], v[154:157], v[212:215], v[72:75]
	s_setprio 0
	s_setprio 1
	v_mfma_f32_16x16x32_bf16 v[116:119], v[158:161], v[174:177], v[116:119]
	v_mfma_f32_16x16x32_bf16 v[112:115], v[166:169], v[174:177], v[112:115]
	v_mfma_f32_16x16x32_bf16 v[100:103], v[158:161], v[182:185], v[100:103]
	v_mfma_f32_16x16x32_bf16 v[96:99], v[166:169], v[182:185], v[96:99]
	v_mfma_f32_16x16x32_bf16 v[84:87], v[158:161], v[200:203], v[84:87]
	v_mfma_f32_16x16x32_bf16 v[80:83], v[166:169], v[200:203], v[80:83]
	v_mfma_f32_16x16x32_bf16 v[68:71], v[158:161], v[208:211], v[68:71]
	v_mfma_f32_16x16x32_bf16 v[64:67], v[166:169], v[208:211], v[64:67]
	v_mfma_f32_16x16x32_bf16 v[116:119], v[162:165], v[178:181], v[116:119]
	v_mfma_f32_16x16x32_bf16 v[112:115], v[170:173], v[178:181], v[112:115]
	v_mfma_f32_16x16x32_bf16 v[100:103], v[162:165], v[186:189], v[100:103]
	v_mfma_f32_16x16x32_bf16 v[96:99], v[170:173], v[186:189], v[96:99]
	v_mfma_f32_16x16x32_bf16 v[84:87], v[162:165], v[204:207], v[84:87]
	v_mfma_f32_16x16x32_bf16 v[80:83], v[170:173], v[204:207], v[80:83]
	v_mfma_f32_16x16x32_bf16 v[68:71], v[162:165], v[212:215], v[68:71]
	v_mfma_f32_16x16x32_bf16 v[64:67], v[170:173], v[212:215], v[64:67]
	s_setprio 0
	s_barrier
; #define PG8_STAGE(bufoff, gbase, voff) do { _Pragma("unroll") for (int _i = 0; _i < 2; ++_i) \
;         __builtin_amdgcn_global_load_lds((const unsigned*)((const char*)(gbase) + (voff)[_i]), (PG8_LAS unsigned*)(lds + (bufoff) + ldsw + _i * 8192), 16, 0, 0); } while (0)
; #define PG8_LDA(dst, b, h) do { _Pragma("unroll") for (int m = 0; m < 4; ++m) _Pragma("unroll") for (int k = 0; k < 2; ++k) dst[m][k] = *(const PG8_LAS bf16x8*)(lds + PG8_SA(b, h) + aoff + m * 2048 + k * 1024); } while (0)
; #define PG8_MMA(ai, bj, At, Bt) do { __builtin_amdgcn_s_setprio(1); _Pragma("unroll") for (int m = 0; m < 4; ++m) _Pragma("unroll") for (int n = 0; n < 2; ++n) _Pragma("unroll") for (int k = 0; k < 2; ++k) \
;         acc[ai][bj][m][n] = __builtin_amdgcn_mfma_f32_16x16x32_bf16(Bt[n][k], At[m][k], acc[ai][bj][m][n], 0, 0, 0); __builtin_amdgcn_s_setprio(0); } while (0)
; #define PG8_WAIT_V(n) asm volatile("s_waitcnt vmcnt(" #n ")" ::: "memory")
; #define PG8_WAIT_L(n) asm volatile("s_waitcnt lgkmcnt(" #n ")" ::: "memory")
; #define PG8_BAR __builtin_amdgcn_s_barrier()
; #define PG8_SCHED __builtin_amdgcn_sched_barrier(0)
; template <class Epi, class Sched, bool ALIGN_EPI = false, bool SP2 = false>
; __device__ __forceinline__ void gemm_phase(PG8_LAS unsigned char* lds, const Gemm g, const Sched& S, const Epi& E, const int tid) {
;     ...
;             PG8_LDA(At, 1, 1); PG8_STAGE(PG8_SB(1, 0), b3, voffB); PG8_STAGE(PG8_SB(1, 1), b3 + hstepB, voffB); PG8_STAGE(PG8_SA(1, 0), a3, voffA);
;             PG8_WAIT_V(8); PG8_WAIT_L(0); PG8_BAR; PG8_MMA(1, 0, At, B0); PG8_MMA(1, 1, At, B1); PG8_BAR; PG8_SCHED;
;     ...
;         if constexpr (ALIGN_EPI) { if (wr == 0) PG8_BAR; }
	s_add_i32 s24, s63, s21
	v_lshl_add_u64 v[190:191], v[190:191], 0, s[60:61]
	s_mov_b32 m0, s24
	ds_read_b128 v[174:177], v145 offset:49152
	ds_read_b128 v[178:181], v145 offset:50176
	ds_read_b128 v[182:185], v145 offset:51200
	ds_read_b128 v[186:189], v145 offset:52224
	ds_read_b128 v[200:203], v145 offset:53248
	ds_read_b128 v[204:207], v145 offset:54272
	ds_read_b128 v[208:211], v145 offset:55296
	ds_read_b128 v[212:215], v145 offset:56320
	global_load_lds_dwordx4 v[190:191], off
	s_add_i32 m0, s24, 0x2000
	s_add_u32 s24, s48, 0x40080
	v_lshl_add_u64 v[190:191], v[216:217], 0, s[60:61]
	s_addc_u32 s25, s49, 0
	s_add_i32 s48, s65, s21
	global_load_lds_dwordx4 v[190:191], off
	v_lshl_add_u64 v[190:191], s[24:25], 0, v[192:193]
	s_mov_b32 m0, s48
	s_nop 0
	global_load_lds_dwordx4 v[190:191], off
	v_lshl_add_u64 v[190:191], s[24:25], 0, v[128:129]
	s_add_i32 m0, s48, 0x2000
	s_nop 0
	global_load_lds_dwordx4 v[190:191], off
	v_lshl_add_u64 v[190:191], v[218:219], 0, s[60:61]
	s_mov_b32 m0, s29
	s_nop 0
	global_load_lds_dwordx4 v[190:191], off
	v_lshl_add_u64 v[190:191], v[220:221], 0, s[60:61]
	s_mov_b32 m0, s40
	s_nop 0
	global_load_lds_dwordx4 v[190:191], off
	s_waitcnt vmcnt(8) lgkmcnt(0)
	s_barrier
	s_setprio 1
	v_mfma_f32_16x16x32_bf16 v[60:63], v[138:141], v[174:177], v[60:63]
	v_mfma_f32_16x16x32_bf16 v[56:59], v[150:153], v[174:177], v[56:59]
	v_mfma_f32_16x16x32_bf16 v[44:47], v[138:141], v[182:185], v[44:47]
	v_mfma_f32_16x16x32_bf16 v[40:43], v[150:153], v[182:185], v[40:43]
	v_mfma_f32_16x16x32_bf16 v[28:31], v[138:141], v[200:203], v[28:31]
	v_mfma_f32_16x16x32_bf16 v[24:27], v[150:153], v[200:203], v[24:27]
	v_mfma_f32_16x16x32_bf16 v[12:15], v[138:141], v[208:211], v[12:15]
	v_mfma_f32_16x16x32_bf16 v[8:11], v[150:153], v[208:211], v[8:11]
	v_mfma_f32_16x16x32_bf16 v[60:63], v[146:149], v[178:181], v[60:63]
	v_mfma_f32_16x16x32_bf16 v[56:59], v[154:157], v[178:181], v[56:59]
	v_mfma_f32_16x16x32_bf16 v[44:47], v[146:149], v[186:189], v[44:47]
	v_mfma_f32_16x16x32_bf16 v[40:43], v[154:157], v[186:189], v[40:43]
	v_mfma_f32_16x16x32_bf16 v[28:31], v[146:149], v[204:207], v[28:31]
	v_mfma_f32_16x16x32_bf16 v[24:27], v[154:157], v[204:207], v[24:27]
	v_mfma_f32_16x16x32_bf16 v[12:15], v[146:149], v[212:215], v[12:15]
	v_mfma_f32_16x16x32_bf16 v[8:11], v[154:157], v[212:215], v[8:11]
	s_setprio 0
	s_setprio 1
	v_mfma_f32_16x16x32_bf16 v[52:55], v[158:161], v[174:177], v[52:55]
	v_mfma_f32_16x16x32_bf16 v[48:51], v[166:169], v[174:177], v[48:51]
	v_mfma_f32_16x16x32_bf16 v[36:39], v[158:161], v[182:185], v[36:39]
	v_mfma_f32_16x16x32_bf16 v[32:35], v[166:169], v[182:185], v[32:35]
	v_mfma_f32_16x16x32_bf16 v[20:23], v[158:161], v[200:203], v[20:23]
	v_mfma_f32_16x16x32_bf16 v[16:19], v[166:169], v[200:203], v[16:19]
	v_mfma_f32_16x16x32_bf16 v[4:7], v[158:161], v[208:211], v[4:7]
	v_mfma_f32_16x16x32_bf16 v[0:3], v[166:169], v[208:211], v[0:3]
	v_mfma_f32_16x16x32_bf16 v[52:55], v[162:165], v[178:181], v[52:55]
	v_mfma_f32_16x16x32_bf16 v[48:51], v[170:173], v[178:181], v[48:51]
	v_mfma_f32_16x16x32_bf16 v[36:39], v[162:165], v[186:189], v[36:39]
	v_mfma_f32_16x16x32_bf16 v[32:35], v[170:173], v[186:189], v[32:35]
	v_mfma_f32_16x16x32_bf16 v[20:23], v[162:165], v[204:207], v[20:23]
	v_mfma_f32_16x16x32_bf16 v[16:19], v[170:173], v[204:207], v[16:19]
	v_mfma_f32_16x16x32_bf16 v[4:7], v[162:165], v[212:215], v[4:7]
	v_mfma_f32_16x16x32_bf16 v[0:3], v[170:173], v[212:215], v[0:3]
	s_setprio 0
	s_barrier
	s_add_i32 s59, s59, 2
	s_add_u32 s55, s55, 0x100
	s_addc_u32 s58, s58, 0
	s_add_u32 s46, s46, 0x100
	s_addc_u32 s47, s47, 0
	s_cmp_gt_u32 s59, 13
	s_cbranch_scc0 .LBB0_36
	s_and_b64 vcc, exec, s[12:13]
	s_cbranch_vccz .LBB0_39
	s_barrier

; #define PG8_STAGE(bufoff, gbase, voff) do { _Pragma("unroll") for (int _i = 0; _i < 2; ++_i) \
;         __builtin_amdgcn_global_load_lds((const unsigned*)((const char*)(gbase) + (voff)[_i]), (PG8_LAS unsigned*)(lds + (bufoff) + ldsw + _i * 8192), 16, 0, 0); } while (0)
; #define PG8_LDA(dst, b, h) do { _Pragma("unroll") for (int m = 0; m < 4; ++m) _Pragma("unroll") for (int k = 0; k < 2; ++k) dst[m][k] = *(const PG8_LAS bf16x8*)(lds + PG8_SA(b, h) + aoff + m * 2048 + k * 1024); } while (0)
; #define PG8_LDB(dst, b, h) do { _Pragma("unroll") for (int n = 0; n < 2; ++n) _Pragma("unroll") for (int k = 0; k < 2; ++k) dst[n][k] = *(const PG8_LAS bf16x8*)(lds + PG8_SB(b, h) + boff + n * 2048 + k * 1024); } while (0)
; #define PG8_MMA(ai, bj, At, Bt) do { __builtin_amdgcn_s_setprio(1); _Pragma("unroll") for (int m = 0; m < 4; ++m) _Pragma("unroll") for (int n = 0; n < 2; ++n) _Pragma("unroll") for (int k = 0; k < 2; ++k) \
;         acc[ai][bj][m][n] = __builtin_amdgcn_mfma_f32_16x16x32_bf16(Bt[n][k], At[m][k], acc[ai][bj][m][n], 0, 0, 0); __builtin_amdgcn_s_setprio(0); } while (0)
; #define PG8_WAIT_V(n) asm volatile("s_waitcnt vmcnt(" #n ")" ::: "memory")
; #define PG8_WAIT_L(n) asm volatile("s_waitcnt lgkmcnt(" #n ")" ::: "memory")
; #define PG8_BAR __builtin_amdgcn_s_barrier()
; #define PG8_SCHED __builtin_amdgcn_sched_barrier(0)
; template <class Epi, class Sched, bool ALIGN_EPI = false, bool SP2 = false>
; __device__ __forceinline__ void gemm_phase(PG8_LAS unsigned char* lds, const Gemm g, const Sched& S, const Epi& E, const int tid) {
;     ...
;             const bool last = (t == nt - 2);
;             const char* a1 = cA + (size_t)(t + 1) * kstep;
;             const char* a2 = last ? nA : cA + (size_t)(t + 2) * kstep; const char* b2 = last ? nB : cB + (size_t)(t + 2) * kstep;
;             const char* a3 = a2 + kstep; const char* b3 = b2 + kstep;
;             if (last && has_next) S.a_ready(nxt);
;             if constexpr (SP2) {
;             PG8_LDB(B0, 0, 0); PG8_LDB(B1, 0, 1); PG8_SCHED; PG8_LDA(At, 0, 0); PG8_STAGE(PG8_SA(1, 1), a1 + hstepA, voffA);
;             PG8_WAIT_V(8); PG8_WAIT_L(0); PG8_BAR; PG8_MMA(0, 0, At, B0); PG8_MMA(0, 1, At, B1); PG8_BAR; PG8_SCHED;
;             PG8_LDA(At, 0, 1); PG8_STAGE(PG8_SB(0, 0), b2, voffB); PG8_STAGE(PG8_SB(0, 1), b2 + hstepB, voffB); PG8_STAGE(PG8_SA(0, 0), a2, voffA);
.LBB0_70:
	s_add_u32 s24, s50, 0xfffc0080
	s_addc_u32 s25, s51, -1
	s_add_i32 s68, 0, 0x10000
	s_cmp_eq_u32 s74, 12
	s_cselect_b32 s55, s19, s25
	s_cselect_b32 s54, s63, s24
	s_cselect_b32 s53, s13, s2
	s_cselect_b32 s52, s65, s78
	s_add_i32 s69, 0, 0x14000
	v_add_u32_e32 v140, s68, v155
	v_add_u32_e32 v166, s69, v155
	ds_read_b128 v[128:131], v140
	ds_read_b128 v[132:135], v140 offset:1024
	ds_read_b128 v[136:139], v140 offset:2048
	ds_read_b128 v[140:143], v140 offset:3072
	ds_read_b128 v[150:153], v166
	ds_read_b128 v[158:161], v166 offset:1024
	ds_read_b128 v[162:165], v166 offset:2048
	ds_read_b128 v[166:169], v166 offset:3072
	v_lshl_add_u64 v[190:191], s[50:51], 0, v[148:149]
	s_add_i32 m0, s21, 0xc000
	ds_read_b128 v[170:173], v157
	ds_read_b128 v[174:177], v157 offset:1024
	ds_read_b128 v[178:181], v157 offset:2048
	ds_read_b128 v[182:185], v157 offset:3072
	ds_read_b128 v[186:189], v157 offset:4096
	ds_read_b128 v[200:203], v157 offset:5120
	ds_read_b128 v[204:207], v157 offset:6144
	ds_read_b128 v[208:211], v157 offset:7168
	global_load_lds_dwordx4 v[190:191], off
	v_lshl_add_u64 v[190:191], s[50:51], 0, v[146:147]
	s_add_i32 m0, s21, 0xe000
	s_nop 0
	global_load_lds_dwordx4 v[190:191], off
	s_waitcnt vmcnt(8) lgkmcnt(0)
	s_barrier
	s_setprio 1
	v_mfma_f32_16x16x32_bf16 v[124:127], v[128:131], v[170:173], v[124:127]
	v_mfma_f32_16x16x32_bf16 v[120:123], v[136:139], v[170:173], v[120:123]
	v_mfma_f32_16x16x32_bf16 v[108:111], v[128:131], v[178:181], v[108:111]
	v_mfma_f32_16x16x32_bf16 v[104:107], v[136:139], v[178:181], v[104:107]
	v_mfma_f32_16x16x32_bf16 v[92:95], v[128:131], v[186:189], v[92:95]
	v_mfma_f32_16x16x32_bf16 v[88:91], v[136:139], v[186:189], v[88:91]
	v_mfma_f32_16x16x32_bf16 v[84:87], v[128:131], v[204:207], v[84:87]
	v_mfma_f32_16x16x32_bf16 v[80:83], v[136:139], v[204:207], v[80:83]
	v_mfma_f32_16x16x32_bf16 v[124:127], v[132:135], v[174:177], v[124:127]
	v_mfma_f32_16x16x32_bf16 v[120:123], v[140:143], v[174:177], v[120:123]
	v_mfma_f32_16x16x32_bf16 v[108:111], v[132:135], v[182:185], v[108:111]
	v_mfma_f32_16x16x32_bf16 v[104:107], v[140:143], v[182:185], v[104:107]
	v_mfma_f32_16x16x32_bf16 v[92:95], v[132:135], v[200:203], v[92:95]
	v_mfma_f32_16x16x32_bf16 v[88:91], v[140:143], v[200:203], v[88:91]
	v_mfma_f32_16x16x32_bf16 v[84:87], v[132:135], v[208:211], v[84:87]
	v_mfma_f32_16x16x32_bf16 v[80:83], v[140:143], v[208:211], v[80:83]
	s_setprio 0
	s_setprio 1
	v_mfma_f32_16x16x32_bf16 v[116:119], v[150:153], v[170:173], v[116:119]
	v_mfma_f32_16x16x32_bf16 v[112:115], v[162:165], v[170:173], v[112:115]
	v_mfma_f32_16x16x32_bf16 v[100:103], v[150:153], v[178:181], v[100:103]
	v_mfma_f32_16x16x32_bf16 v[96:99], v[162:165], v[178:181], v[96:99]
	v_mfma_f32_16x16x32_bf16 v[76:79], v[150:153], v[186:189], v[76:79]
	v_mfma_f32_16x16x32_bf16 v[72:75], v[162:165], v[186:189], v[72:75]
	v_mfma_f32_16x16x32_bf16 v[68:71], v[150:153], v[204:207], v[68:71]
	v_mfma_f32_16x16x32_bf16 v[64:67], v[162:165], v[204:207], v[64:67]
	v_mfma_f32_16x16x32_bf16 v[116:119], v[158:161], v[174:177], v[116:119]
	v_mfma_f32_16x16x32_bf16 v[112:115], v[166:169], v[174:177], v[112:115]
	v_mfma_f32_16x16x32_bf16 v[100:103], v[158:161], v[182:185], v[100:103]
	v_mfma_f32_16x16x32_bf16 v[96:99], v[166:169], v[182:185], v[96:99]
	v_mfma_f32_16x16x32_bf16 v[76:79], v[158:161], v[200:203], v[76:79]
	v_mfma_f32_16x16x32_bf16 v[72:75], v[166:169], v[200:203], v[72:75]
	v_mfma_f32_16x16x32_bf16 v[68:71], v[158:161], v[208:211], v[68:71]
	v_mfma_f32_16x16x32_bf16 v[64:67], v[166:169], v[208:211], v[64:67]
	s_setprio 0
	s_barrier
	s_add_i32 s24, s68, s20
	v_lshl_add_u64 v[190:191], s[52:53], 0, v[192:193]
	s_mov_b32 m0, s24
	ds_read_b128 v[170:173], v157 offset:16384
	ds_read_b128 v[174:177], v157 offset:17408
	ds_read_b128 v[178:181], v157 offset:18432
	ds_read_b128 v[182:185], v157 offset:19456
	ds_read_b128 v[186:189], v157 offset:20480
	ds_read_b128 v[200:203], v157 offset:21504
	ds_read_b128 v[204:207], v157 offset:22528
	ds_read_b128 v[208:211], v157 offset:23552
	global_load_lds_dwordx4 v[190:191], off
	s_add_i32 m0, s24, 0x2000
	s_add_u32 s24, s52, 0x40000
	v_lshl_add_u64 v[212:213], s[52:53], 0, v[144:145]
	s_addc_u32 s25, s53, 0
	s_add_i32 s68, s69, s20
	global_load_lds_dwordx4 v[212:213], off
	v_lshl_add_u64 v[214:215], s[24:25], 0, v[192:193]
	s_mov_b32 m0, s68
	v_lshl_add_u64 v[216:217], s[54:55], 0, v[144:145]
	global_load_lds_dwordx4 v[214:215], off
	v_lshl_add_u64 v[214:215], s[24:25], 0, v[144:145]
	s_add_i32 m0, s68, 0x2000
	s_nop 0
	global_load_lds_dwordx4 v[214:215], off
	v_lshl_add_u64 v[214:215], s[54:55], 0, v[192:193]
	s_mov_b32 m0, s21
	s_nop 0
	global_load_lds_dwordx4 v[214:215], off
	s_mov_b32 m0, s26
	s_nop 0
	global_load_lds_dwordx4 v[216:217], off
	s_waitcnt vmcnt(8) lgkmcnt(0)
	s_barrier
; #define PG8_STAGE(bufoff, gbase, voff) do { _Pragma("unroll") for (int _i = 0; _i < 2; ++_i) \
;         __builtin_amdgcn_global_load_lds((const unsigned*)((const char*)(gbase) + (voff)[_i]), (PG8_LAS unsigned*)(lds + (bufoff) + ldsw + _i * 8192), 16, 0, 0); } while (0)
; #define PG8_LDA(dst, b, h) do { _Pragma("unroll") for (int m = 0; m < 4; ++m) _Pragma("unroll") for (int k = 0; k < 2; ++k) dst[m][k] = *(const PG8_LAS bf16x8*)(lds + PG8_SA(b, h) + aoff + m * 2048 + k * 1024); } while (0)
; #define PG8_LDB(dst, b, h) do { _Pragma("unroll") for (int n = 0; n < 2; ++n) _Pragma("unroll") for (int k = 0; k < 2; ++k) dst[n][k] = *(const PG8_LAS bf16x8*)(lds + PG8_SB(b, h) + boff + n * 2048 + k * 1024); } while (0)
; #define PG8_MMA(ai, bj, At, Bt) do { __builtin_amdgcn_s_setprio(1); _Pragma("unroll") for (int m = 0; m < 4; ++m) _Pragma("unroll") for (int n = 0; n < 2; ++n) _Pragma("unroll") for (int k = 0; k < 2; ++k) \
;         acc[ai][bj][m][n] = __builtin_amdgcn_mfma_f32_16x16x32_bf16(Bt[n][k], At[m][k], acc[ai][bj][m][n], 0, 0, 0); __builtin_amdgcn_s_setprio(0); } while (0)
; #define PG8_WAIT_V(n) asm volatile("s_waitcnt vmcnt(" #n ")" ::: "memory")
; #define PG8_WAIT_L(n) asm volatile("s_waitcnt lgkmcnt(" #n ")" ::: "memory")
; #define PG8_BAR __builtin_amdgcn_s_barrier()
; #define PG8_SCHED __builtin_amdgcn_sched_barrier(0)
; template <class Epi, class Sched, bool ALIGN_EPI = false, bool SP2 = false>
; __device__ __forceinline__ void gemm_phase(PG8_LAS unsigned char* lds, const Gemm g, const Sched& S, const Epi& E, const int tid) {
;     ...
;             PG8_WAIT_V(8); PG8_WAIT_L(0); PG8_BAR; PG8_MMA(1, 0, At, B0); PG8_MMA(1, 1, At, B1); PG8_BAR; PG8_SCHED;
;             PG8_LDB(B0, 1, 0); PG8_LDB(B1, 1, 1); PG8_SCHED; PG8_LDA(At, 1, 0); PG8_STAGE(PG8_SA(0, 1), a2 + hstepA, voffA);
;             PG8_WAIT_V(8); PG8_WAIT_L(0); PG8_BAR; PG8_MMA(0, 0, At, B0); PG8_MMA(0, 1, At, B1); PG8_BAR; PG8_SCHED;
	s_setprio 1
	v_mfma_f32_16x16x32_bf16 v[60:63], v[128:131], v[170:173], v[60:63]
	v_mfma_f32_16x16x32_bf16 v[56:59], v[136:139], v[170:173], v[56:59]
	v_mfma_f32_16x16x32_bf16 v[52:55], v[128:131], v[178:181], v[52:55]
	v_mfma_f32_16x16x32_bf16 v[40:43], v[136:139], v[178:181], v[40:43]
	v_mfma_f32_16x16x32_bf16 v[28:31], v[128:131], v[186:189], v[28:31]
	v_mfma_f32_16x16x32_bf16 v[24:27], v[136:139], v[186:189], v[24:27]
	v_mfma_f32_16x16x32_bf16 v[16:19], v[128:131], v[204:207], v[16:19]
	v_mfma_f32_16x16x32_bf16 v[8:11], v[136:139], v[204:207], v[8:11]
	v_mfma_f32_16x16x32_bf16 v[60:63], v[132:135], v[174:177], v[60:63]
	v_mfma_f32_16x16x32_bf16 v[56:59], v[140:143], v[174:177], v[56:59]
	v_mfma_f32_16x16x32_bf16 v[52:55], v[132:135], v[182:185], v[52:55]
	v_mfma_f32_16x16x32_bf16 v[40:43], v[140:143], v[182:185], v[40:43]
	v_mfma_f32_16x16x32_bf16 v[28:31], v[132:135], v[200:203], v[28:31]
	v_mfma_f32_16x16x32_bf16 v[24:27], v[140:143], v[200:203], v[24:27]
	v_mfma_f32_16x16x32_bf16 v[16:19], v[132:135], v[208:211], v[16:19]
	v_mfma_f32_16x16x32_bf16 v[8:11], v[140:143], v[208:211], v[8:11]
	s_setprio 0
	s_setprio 1
	v_mfma_f32_16x16x32_bf16 v[48:51], v[150:153], v[170:173], v[48:51]
	v_mfma_f32_16x16x32_bf16 v[44:47], v[162:165], v[170:173], v[44:47]
	v_mfma_f32_16x16x32_bf16 v[36:39], v[150:153], v[178:181], v[36:39]
	v_mfma_f32_16x16x32_bf16 v[32:35], v[162:165], v[178:181], v[32:35]
	v_mfma_f32_16x16x32_bf16 v[20:23], v[150:153], v[186:189], v[20:23]
	v_mfma_f32_16x16x32_bf16 v[12:15], v[162:165], v[186:189], v[12:15]
	v_mfma_f32_16x16x32_bf16 v[4:7], v[150:153], v[204:207], v[4:7]
	v_mfma_f32_16x16x32_bf16 v[0:3], v[162:165], v[204:207], v[0:3]
	v_mfma_f32_16x16x32_bf16 v[48:51], v[158:161], v[174:177], v[48:51]
	v_mfma_f32_16x16x32_bf16 v[44:47], v[166:169], v[174:177], v[44:47]
	v_mfma_f32_16x16x32_bf16 v[36:39], v[158:161], v[182:185], v[36:39]
	v_mfma_f32_16x16x32_bf16 v[32:35], v[166:169], v[182:185], v[32:35]
	v_mfma_f32_16x16x32_bf16 v[20:23], v[158:161], v[200:203], v[20:23]
	v_mfma_f32_16x16x32_bf16 v[12:15], v[166:169], v[200:203], v[12:15]
	v_mfma_f32_16x16x32_bf16 v[4:7], v[158:161], v[208:211], v[4:7]
	v_mfma_f32_16x16x32_bf16 v[0:3], v[166:169], v[208:211], v[0:3]
	s_setprio 0
	s_barrier
	s_add_i32 s68, 0, 0x18000
	s_add_i32 s69, 0, 0x1c000
	v_add_u32_e32 v140, s68, v155
	v_add_u32_e32 v166, s69, v155
	ds_read_b128 v[128:131], v140
	ds_read_b128 v[132:135], v140 offset:1024
	ds_read_b128 v[136:139], v140 offset:2048
	ds_read_b128 v[140:143], v140 offset:3072
	ds_read_b128 v[150:153], v166
	ds_read_b128 v[158:161], v166 offset:1024
	ds_read_b128 v[162:165], v166 offset:2048
	ds_read_b128 v[166:169], v166 offset:3072
	s_add_u32 s24, s54, 0x40000
	s_addc_u32 s25, s55, 0
	s_mov_b32 m0, s27
	v_lshl_add_u64 v[218:219], s[24:25], 0, v[192:193]
	ds_read_b128 v[170:173], v157 offset:32768
	ds_read_b128 v[174:177], v157 offset:33792
	ds_read_b128 v[178:181], v157 offset:34816
	ds_read_b128 v[182:185], v157 offset:35840
	ds_read_b128 v[186:189], v157 offset:36864
	ds_read_b128 v[200:203], v157 offset:37888
	ds_read_b128 v[204:207], v157 offset:38912
	ds_read_b128 v[208:211], v157 offset:39936
	global_load_lds_dwordx4 v[218:219], off
	v_lshl_add_u64 v[218:219], s[24:25], 0, v[144:145]
	s_mov_b32 m0, s28
	s_nop 0
	global_load_lds_dwordx4 v[218:219], off
	s_waitcnt vmcnt(8) lgkmcnt(0)
	s_barrier
	s_setprio 1
	v_mfma_f32_16x16x32_bf16 v[124:127], v[128:131], v[170:173], v[124:127]
	v_mfma_f32_16x16x32_bf16 v[120:123], v[136:139], v[170:173], v[120:123]
	v_mfma_f32_16x16x32_bf16 v[108:111], v[128:131], v[178:181], v[108:111]
	v_mfma_f32_16x16x32_bf16 v[104:107], v[136:139], v[178:181], v[104:107]
	v_mfma_f32_16x16x32_bf16 v[92:95], v[128:131], v[186:189], v[92:95]
	v_mfma_f32_16x16x32_bf16 v[88:91], v[136:139], v[186:189], v[88:91]
	v_mfma_f32_16x16x32_bf16 v[84:87], v[128:131], v[204:207], v[84:87]
	v_mfma_f32_16x16x32_bf16 v[80:83], v[136:139], v[204:207], v[80:83]
	v_mfma_f32_16x16x32_bf16 v[124:127], v[132:135], v[174:177], v[124:127]
	v_mfma_f32_16x16x32_bf16 v[120:123], v[140:143], v[174:177], v[120:123]
	v_mfma_f32_16x16x32_bf16 v[108:111], v[132:135], v[182:185], v[108:111]
	v_mfma_f32_16x16x32_bf16 v[104:107], v[140:143], v[182:185], v[104:107]
	v_mfma_f32_16x16x32_bf16 v[92:95], v[132:135], v[200:203], v[92:95]
	v_mfma_f32_16x16x32_bf16 v[88:91], v[140:143], v[200:203], v[88:91]
	v_mfma_f32_16x16x32_bf16 v[84:87], v[132:135], v[208:211], v[84:87]
	v_mfma_f32_16x16x32_bf16 v[80:83], v[140:143], v[208:211], v[80:83]
	s_setprio 0
	s_setprio 1
	v_mfma_f32_16x16x32_bf16 v[116:119], v[150:153], v[170:173], v[116:119]
	v_mfma_f32_16x16x32_bf16 v[112:115], v[162:165], v[170:173], v[112:115]
	v_mfma_f32_16x16x32_bf16 v[100:103], v[150:153], v[178:181], v[100:103]
	v_mfma_f32_16x16x32_bf16 v[96:99], v[162:165], v[178:181], v[96:99]
	v_mfma_f32_16x16x32_bf16 v[76:79], v[150:153], v[186:189], v[76:79]
	v_mfma_f32_16x16x32_bf16 v[72:75], v[162:165], v[186:189], v[72:75]
	v_mfma_f32_16x16x32_bf16 v[68:71], v[150:153], v[204:207], v[68:71]
	v_mfma_f32_16x16x32_bf16 v[64:67], v[162:165], v[204:207], v[64:67]
	v_mfma_f32_16x16x32_bf16 v[116:119], v[158:161], v[174:177], v[116:119]
	v_mfma_f32_16x16x32_bf16 v[112:115], v[166:169], v[174:177], v[112:115]
	v_mfma_f32_16x16x32_bf16 v[100:103], v[158:161], v[182:185], v[100:103]
	v_mfma_f32_16x16x32_bf16 v[96:99], v[166:169], v[182:185], v[96:99]
	v_mfma_f32_16x16x32_bf16 v[76:79], v[158:161], v[200:203], v[76:79]
	v_mfma_f32_16x16x32_bf16 v[72:75], v[166:169], v[200:203], v[72:75]
	v_mfma_f32_16x16x32_bf16 v[68:71], v[158:161], v[208:211], v[68:71]
	v_mfma_f32_16x16x32_bf16 v[64:67], v[166:169], v[208:211], v[64:67]
	s_setprio 0
	s_barrier
; #define PG8_STAGE(bufoff, gbase, voff) do { _Pragma("unroll") for (int _i = 0; _i < 2; ++_i) \
;         __builtin_amdgcn_global_load_lds((const unsigned*)((const char*)(gbase) + (voff)[_i]), (PG8_LAS unsigned*)(lds + (bufoff) + ldsw + _i * 8192), 16, 0, 0); } while (0)
; #define PG8_LDA(dst, b, h) do { _Pragma("unroll") for (int m = 0; m < 4; ++m) _Pragma("unroll") for (int k = 0; k < 2; ++k) dst[m][k] = *(const PG8_LAS bf16x8*)(lds + PG8_SA(b, h) + aoff + m * 2048 + k * 1024); } while (0)
; #define PG8_MMA(ai, bj, At, Bt) do { __builtin_amdgcn_s_setprio(1); _Pragma("unroll") for (int m = 0; m < 4; ++m) _Pragma("unroll") for (int n = 0; n < 2; ++n) _Pragma("unroll") for (int k = 0; k < 2; ++k) \
;         acc[ai][bj][m][n] = __builtin_amdgcn_mfma_f32_16x16x32_bf16(Bt[n][k], At[m][k], acc[ai][bj][m][n], 0, 0, 0); __builtin_amdgcn_s_setprio(0); } while (0)
; #define PG8_WAIT_V(n) asm volatile("s_waitcnt vmcnt(" #n ")" ::: "memory")
; #define PG8_WAIT_L(n) asm volatile("s_waitcnt lgkmcnt(" #n ")" ::: "memory")
; #define PG8_BAR __builtin_amdgcn_s_barrier()
; #define PG8_SCHED __builtin_amdgcn_sched_barrier(0)
; template <class Epi, class Sched, bool ALIGN_EPI = false, bool SP2 = false>
; __device__ __forceinline__ void gemm_phase(PG8_LAS unsigned char* lds, const Gemm g, const Sched& S, const Epi& E, const int tid) {
;     ...
;             PG8_LDA(At, 1, 1); PG8_STAGE(PG8_SB(1, 0), b3, voffB); PG8_STAGE(PG8_SB(1, 1), b3 + hstepB, voffB); PG8_STAGE(PG8_SA(1, 0), a3, voffA);
;             PG8_WAIT_V(8); PG8_WAIT_L(0); PG8_BAR; PG8_MMA(1, 0, At, B0); PG8_MMA(1, 1, At, B1); PG8_BAR; PG8_SCHED;
;     ...
;         if constexpr (ALIGN_EPI) { if (wr == 0) PG8_BAR; }
	s_add_i32 s24, s68, s20
	v_lshl_add_u64 v[190:191], v[190:191], 0, s[60:61]
	s_mov_b32 m0, s24
	ds_read_b128 v[170:173], v157 offset:49152
	ds_read_b128 v[174:177], v157 offset:50176
	ds_read_b128 v[178:181], v157 offset:51200
	ds_read_b128 v[182:185], v157 offset:52224
	ds_read_b128 v[186:189], v157 offset:53248
	ds_read_b128 v[200:203], v157 offset:54272
	ds_read_b128 v[204:207], v157 offset:55296
	ds_read_b128 v[208:211], v157 offset:56320
	global_load_lds_dwordx4 v[190:191], off
	s_add_i32 m0, s24, 0x2000
	s_add_u32 s24, s52, 0x40080
	v_lshl_add_u64 v[190:191], v[212:213], 0, s[60:61]
	s_addc_u32 s25, s53, 0
	s_add_i32 s52, s69, s20
	global_load_lds_dwordx4 v[190:191], off
	v_lshl_add_u64 v[190:191], s[24:25], 0, v[192:193]
	s_mov_b32 m0, s52
	s_nop 0
	global_load_lds_dwordx4 v[190:191], off
	v_lshl_add_u64 v[190:191], s[24:25], 0, v[144:145]
	s_add_i32 m0, s52, 0x2000
	s_nop 0
	global_load_lds_dwordx4 v[190:191], off
	v_lshl_add_u64 v[190:191], v[214:215], 0, s[60:61]
	s_mov_b32 m0, s39
	s_nop 0
	global_load_lds_dwordx4 v[190:191], off
	v_lshl_add_u64 v[190:191], v[216:217], 0, s[60:61]
	s_mov_b32 m0, s40
	s_nop 0
	global_load_lds_dwordx4 v[190:191], off
	s_waitcnt vmcnt(8) lgkmcnt(0)
	s_barrier
	s_setprio 1
	v_mfma_f32_16x16x32_bf16 v[60:63], v[128:131], v[170:173], v[60:63]
	v_mfma_f32_16x16x32_bf16 v[56:59], v[136:139], v[170:173], v[56:59]
	v_mfma_f32_16x16x32_bf16 v[52:55], v[128:131], v[178:181], v[52:55]
	v_mfma_f32_16x16x32_bf16 v[40:43], v[136:139], v[178:181], v[40:43]
	v_mfma_f32_16x16x32_bf16 v[28:31], v[128:131], v[186:189], v[28:31]
	v_mfma_f32_16x16x32_bf16 v[24:27], v[136:139], v[186:189], v[24:27]
	v_mfma_f32_16x16x32_bf16 v[16:19], v[128:131], v[204:207], v[16:19]
	v_mfma_f32_16x16x32_bf16 v[8:11], v[136:139], v[204:207], v[8:11]
	v_mfma_f32_16x16x32_bf16 v[60:63], v[132:135], v[174:177], v[60:63]
	v_mfma_f32_16x16x32_bf16 v[56:59], v[140:143], v[174:177], v[56:59]
	v_mfma_f32_16x16x32_bf16 v[52:55], v[132:135], v[182:185], v[52:55]
	v_mfma_f32_16x16x32_bf16 v[40:43], v[140:143], v[182:185], v[40:43]
	v_mfma_f32_16x16x32_bf16 v[28:31], v[132:135], v[200:203], v[28:31]
	v_mfma_f32_16x16x32_bf16 v[24:27], v[140:143], v[200:203], v[24:27]
	v_mfma_f32_16x16x32_bf16 v[16:19], v[132:135], v[208:211], v[16:19]
	v_mfma_f32_16x16x32_bf16 v[8:11], v[140:143], v[208:211], v[8:11]
	s_setprio 0
	s_setprio 1
	v_mfma_f32_16x16x32_bf16 v[48:51], v[150:153], v[170:173], v[48:51]
	v_mfma_f32_16x16x32_bf16 v[44:47], v[162:165], v[170:173], v[44:47]
	v_mfma_f32_16x16x32_bf16 v[36:39], v[150:153], v[178:181], v[36:39]
	v_mfma_f32_16x16x32_bf16 v[32:35], v[162:165], v[178:181], v[32:35]
	v_mfma_f32_16x16x32_bf16 v[20:23], v[150:153], v[186:189], v[20:23]
	v_mfma_f32_16x16x32_bf16 v[12:15], v[162:165], v[186:189], v[12:15]
	v_mfma_f32_16x16x32_bf16 v[4:7], v[150:153], v[204:207], v[4:7]
	v_mfma_f32_16x16x32_bf16 v[0:3], v[162:165], v[204:207], v[0:3]
	v_mfma_f32_16x16x32_bf16 v[48:51], v[158:161], v[174:177], v[48:51]
	v_mfma_f32_16x16x32_bf16 v[44:47], v[166:169], v[174:177], v[44:47]
	v_mfma_f32_16x16x32_bf16 v[36:39], v[158:161], v[182:185], v[36:39]
	v_mfma_f32_16x16x32_bf16 v[32:35], v[166:169], v[182:185], v[32:35]
	v_mfma_f32_16x16x32_bf16 v[20:23], v[158:161], v[200:203], v[20:23]
	v_mfma_f32_16x16x32_bf16 v[12:15], v[166:169], v[200:203], v[12:15]
	v_mfma_f32_16x16x32_bf16 v[4:7], v[158:161], v[208:211], v[4:7]
	v_mfma_f32_16x16x32_bf16 v[0:3], v[166:169], v[208:211], v[0:3]
	s_setprio 0
	s_barrier
	s_add_i32 s74, s74, 2
	s_add_u32 s78, s78, 0x100
	s_addc_u32 s2, s2, 0
	s_add_u32 s50, s50, 0x100
	s_addc_u32 s51, s51, 0
	s_cmp_gt_u32 s74, 13
	s_cbranch_scc0 .LBB0_70
	s_and_b64 vcc, exec, s[10:11]
	s_cbranch_vccz .LBB0_73
	s_barrier

; #define PG8_STAGE(bufoff, gbase, voff) do { _Pragma("unroll") for (int _i = 0; _i < 2; ++_i) \
;         __builtin_amdgcn_global_load_lds((const unsigned*)((const char*)(gbase) + (voff)[_i]), (PG8_LAS unsigned*)(lds + (bufoff) + ldsw + _i * 8192), 16, 0, 0); } while (0)
; #define PG8_LDA(dst, b, h) do { _Pragma("unroll") for (int m = 0; m < 4; ++m) _Pragma("unroll") for (int k = 0; k < 2; ++k) dst[m][k] = *(const PG8_LAS bf16x8*)(lds + PG8_SA(b, h) + aoff + m * 2048 + k * 1024); } while (0)
; #define PG8_LDB(dst, b, h) do { _Pragma("unroll") for (int n = 0; n < 2; ++n) _Pragma("unroll") for (int k = 0; k < 2; ++k) dst[n][k] = *(const PG8_LAS bf16x8*)(lds + PG8_SB(b, h) + boff + n * 2048 + k * 1024); } while (0)
; #define PG8_MMA(ai, bj, At, Bt) do { __builtin_amdgcn_s_setprio(1); _Pragma("unroll") for (int m = 0; m < 4; ++m) _Pragma("unroll") for (int n = 0; n < 2; ++n) _Pragma("unroll") for (int k = 0; k < 2; ++k) \
;         acc[ai][bj][m][n] = __builtin_amdgcn_mfma_f32_16x16x32_bf16(Bt[n][k], At[m][k], acc[ai][bj][m][n], 0, 0, 0); __builtin_amdgcn_s_setprio(0); } while (0)
; #define PG8_WAIT_V(n) asm volatile("s_waitcnt vmcnt(" #n ")" ::: "memory")
; #define PG8_WAIT_L(n) asm volatile("s_waitcnt lgkmcnt(" #n ")" ::: "memory")
; #define PG8_BAR __builtin_amdgcn_s_barrier()
; #define PG8_SCHED __builtin_amdgcn_sched_barrier(0)
; template <class Epi, class Sched, bool ALIGN_EPI = false, bool SP2 = false>
; __device__ __forceinline__ void gemm_phase(PG8_LAS unsigned char* lds, const Gemm g, const Sched& S, const Epi& E, const int tid) {
;     ...
;             const bool last = (t == nt - 2);
;             const char* a1 = cA + (size_t)(t + 1) * kstep;
;             const char* a2 = last ? nA : cA + (size_t)(t + 2) * kstep; const char* b2 = last ? nB : cB + (size_t)(t + 2) * kstep;
;             const char* a3 = a2 + kstep; const char* b3 = b2 + kstep;
;             if (last && has_next) S.a_ready(nxt);
;             if constexpr (SP2) {
;             PG8_LDB(B0, 0, 0); PG8_LDB(B1, 0, 1); PG8_SCHED; PG8_LDA(At, 0, 0); PG8_STAGE(PG8_SA(1, 1), a1 + hstepA, voffA);
;             PG8_WAIT_V(8); PG8_WAIT_L(0); PG8_BAR; PG8_MMA(0, 0, At, B0); PG8_MMA(0, 1, At, B1); PG8_BAR; PG8_SCHED;
;             PG8_LDA(At, 0, 1); PG8_STAGE(PG8_SB(0, 0), b2, voffB); PG8_STAGE(PG8_SB(0, 1), b2 + hstepB, voffB); PG8_STAGE(PG8_SA(0, 0), a2, voffA);
.LBB0_90:
	s_add_u32 s25, s6, 0xfffe0080
	s_addc_u32 s68, s7, -1
	s_add_i32 s69, 0, 0x10000
	s_cmp_eq_u32 s24, 4
	s_cselect_b32 s89, s55, s68
	s_cselect_b32 s88, vcc_lo, s25
	s_cselect_b32 s87, s53, s74
	s_cselect_b32 s86, vcc_hi, s2
	s_add_i32 s25, 0, 0x14000
	v_add_u32_e32 v92, s69, v237
	v_add_u32_e32 v132, s25, v237
	ds_read_b128 v[64:67], v92
	ds_read_b128 v[76:79], v92 offset:1024
	ds_read_b128 v[80:83], v92 offset:2048
	ds_read_b128 v[92:95], v92 offset:3072
	ds_read_b128 v[104:107], v132
	ds_read_b128 v[116:119], v132 offset:1024
	ds_read_b128 v[128:131], v132 offset:2048
	ds_read_b128 v[132:135], v132 offset:3072
	v_lshl_add_u64 v[210:211], s[6:7], 0, v[208:209]
	s_add_i32 m0, s17, 0xc000
	ds_read_b128 v[160:163], v239
	ds_read_b128 v[164:167], v239 offset:1024
	ds_read_b128 v[168:171], v239 offset:2048
	ds_read_b128 v[172:175], v239 offset:3072
	ds_read_b128 v[176:179], v239 offset:4096
	ds_read_b128 v[180:183], v239 offset:5120
	ds_read_b128 v[184:187], v239 offset:6144
	ds_read_b128 v[188:191], v239 offset:7168
	global_load_lds_dwordx4 v[210:211], off
	v_lshl_add_u64 v[210:211], s[6:7], 0, v[206:207]
	s_add_i32 m0, s17, 0xe000
	s_nop 0
	global_load_lds_dwordx4 v[210:211], off
	s_waitcnt vmcnt(8) lgkmcnt(0)
	s_barrier
	s_setprio 1
	v_mfma_f32_16x16x32_bf16 v[156:159], v[64:67], v[160:163], v[156:159]
	v_mfma_f32_16x16x32_bf16 v[152:155], v[80:83], v[160:163], v[152:155]
	v_mfma_f32_16x16x32_bf16 v[140:143], v[64:67], v[168:171], v[140:143]
	v_mfma_f32_16x16x32_bf16 v[136:139], v[80:83], v[168:171], v[136:139]
	v_mfma_f32_16x16x32_bf16 v[112:115], v[64:67], v[176:179], v[112:115]
	v_mfma_f32_16x16x32_bf16 v[108:111], v[80:83], v[176:179], v[108:111]
	v_mfma_f32_16x16x32_bf16 v[88:91], v[64:67], v[184:187], v[88:91]
	v_mfma_f32_16x16x32_bf16 v[84:87], v[80:83], v[184:187], v[84:87]
	v_mfma_f32_16x16x32_bf16 v[156:159], v[76:79], v[164:167], v[156:159]
	v_mfma_f32_16x16x32_bf16 v[152:155], v[92:95], v[164:167], v[152:155]
	v_mfma_f32_16x16x32_bf16 v[140:143], v[76:79], v[172:175], v[140:143]
	v_mfma_f32_16x16x32_bf16 v[136:139], v[92:95], v[172:175], v[136:139]
	v_mfma_f32_16x16x32_bf16 v[112:115], v[76:79], v[180:183], v[112:115]
	v_mfma_f32_16x16x32_bf16 v[108:111], v[92:95], v[180:183], v[108:111]
	v_mfma_f32_16x16x32_bf16 v[88:91], v[76:79], v[188:191], v[88:91]
	v_mfma_f32_16x16x32_bf16 v[84:87], v[92:95], v[188:191], v[84:87]
	s_setprio 0
	s_setprio 1
	v_mfma_f32_16x16x32_bf16 v[148:151], v[104:107], v[160:163], v[148:151]
	v_mfma_f32_16x16x32_bf16 v[144:147], v[128:131], v[160:163], v[144:147]
	v_mfma_f32_16x16x32_bf16 v[124:127], v[104:107], v[168:171], v[124:127]
	v_mfma_f32_16x16x32_bf16 v[120:123], v[128:131], v[168:171], v[120:123]
	v_mfma_f32_16x16x32_bf16 v[100:103], v[104:107], v[176:179], v[100:103]
	v_mfma_f32_16x16x32_bf16 v[96:99], v[128:131], v[176:179], v[96:99]
	v_mfma_f32_16x16x32_bf16 v[72:75], v[104:107], v[184:187], v[72:75]
	v_mfma_f32_16x16x32_bf16 v[68:71], v[128:131], v[184:187], v[68:71]
	v_mfma_f32_16x16x32_bf16 v[148:151], v[116:119], v[164:167], v[148:151]
	v_mfma_f32_16x16x32_bf16 v[144:147], v[132:135], v[164:167], v[144:147]
	v_mfma_f32_16x16x32_bf16 v[124:127], v[116:119], v[172:175], v[124:127]
	v_mfma_f32_16x16x32_bf16 v[120:123], v[132:135], v[172:175], v[120:123]
	v_mfma_f32_16x16x32_bf16 v[100:103], v[116:119], v[180:183], v[100:103]
	v_mfma_f32_16x16x32_bf16 v[96:99], v[132:135], v[180:183], v[96:99]
	v_mfma_f32_16x16x32_bf16 v[72:75], v[116:119], v[188:191], v[72:75]
	v_mfma_f32_16x16x32_bf16 v[68:71], v[132:135], v[188:191], v[68:71]
	s_setprio 0
	s_barrier
	s_add_i32 s68, s69, s16
	v_lshl_add_u64 v[210:211], s[86:87], 0, v[192:193]
	s_mov_b32 m0, s68
	ds_read_b128 v[160:163], v239 offset:16384
	ds_read_b128 v[164:167], v239 offset:17408
	ds_read_b128 v[168:171], v239 offset:18432
	ds_read_b128 v[172:175], v239 offset:19456
	ds_read_b128 v[176:179], v239 offset:20480
	ds_read_b128 v[180:183], v239 offset:21504
	ds_read_b128 v[184:187], v239 offset:22528
	ds_read_b128 v[188:191], v239 offset:23552
	global_load_lds_dwordx4 v[210:211], off
	s_add_i32 m0, s68, 0x2000
	s_add_u32 s68, s86, 0x20000
	v_lshl_add_u64 v[212:213], s[86:87], 0, v[204:205]
	s_addc_u32 s69, s87, 0
	s_add_i32 s25, s25, s16
	global_load_lds_dwordx4 v[212:213], off
	v_lshl_add_u64 v[214:215], s[68:69], 0, v[192:193]
	s_mov_b32 m0, s25
	v_lshl_add_u64 v[216:217], s[88:89], 0, v[202:203]
	global_load_lds_dwordx4 v[214:215], off
	v_lshl_add_u64 v[214:215], s[68:69], 0, v[204:205]
	s_add_i32 m0, s25, 0x2000
	s_nop 0
	global_load_lds_dwordx4 v[214:215], off
	v_lshl_add_u64 v[214:215], s[88:89], 0, v[200:201]
	s_mov_b32 m0, s17
	s_nop 0
	global_load_lds_dwordx4 v[214:215], off
	s_mov_b32 m0, s38
	s_nop 0
	global_load_lds_dwordx4 v[216:217], off
	s_waitcnt vmcnt(8) lgkmcnt(0)
	s_barrier
; #define PG8_STAGE(bufoff, gbase, voff) do { _Pragma("unroll") for (int _i = 0; _i < 2; ++_i) \
;         __builtin_amdgcn_global_load_lds((const unsigned*)((const char*)(gbase) + (voff)[_i]), (PG8_LAS unsigned*)(lds + (bufoff) + ldsw + _i * 8192), 16, 0, 0); } while (0)
; #define PG8_LDA(dst, b, h) do { _Pragma("unroll") for (int m = 0; m < 4; ++m) _Pragma("unroll") for (int k = 0; k < 2; ++k) dst[m][k] = *(const PG8_LAS bf16x8*)(lds + PG8_SA(b, h) + aoff + m * 2048 + k * 1024); } while (0)
; #define PG8_LDB(dst, b, h) do { _Pragma("unroll") for (int n = 0; n < 2; ++n) _Pragma("unroll") for (int k = 0; k < 2; ++k) dst[n][k] = *(const PG8_LAS bf16x8*)(lds + PG8_SB(b, h) + boff + n * 2048 + k * 1024); } while (0)
; #define PG8_MMA(ai, bj, At, Bt) do { __builtin_amdgcn_s_setprio(1); _Pragma("unroll") for (int m = 0; m < 4; ++m) _Pragma("unroll") for (int n = 0; n < 2; ++n) _Pragma("unroll") for (int k = 0; k < 2; ++k) \
;         acc[ai][bj][m][n] = __builtin_amdgcn_mfma_f32_16x16x32_bf16(Bt[n][k], At[m][k], acc[ai][bj][m][n], 0, 0, 0); __builtin_amdgcn_s_setprio(0); } while (0)
; #define PG8_WAIT_V(n) asm volatile("s_waitcnt vmcnt(" #n ")" ::: "memory")
; #define PG8_WAIT_L(n) asm volatile("s_waitcnt lgkmcnt(" #n ")" ::: "memory")
; #define PG8_BAR __builtin_amdgcn_s_barrier()
; #define PG8_SCHED __builtin_amdgcn_sched_barrier(0)
; template <class Epi, class Sched, bool ALIGN_EPI = false, bool SP2 = false>
; __device__ __forceinline__ void gemm_phase(PG8_LAS unsigned char* lds, const Gemm g, const Sched& S, const Epi& E, const int tid) {
;     ...
;             PG8_WAIT_V(8); PG8_WAIT_L(0); PG8_BAR; PG8_MMA(1, 0, At, B0); PG8_MMA(1, 1, At, B1); PG8_BAR; PG8_SCHED;
;             PG8_LDB(B0, 1, 0); PG8_LDB(B1, 1, 1); PG8_SCHED; PG8_LDA(At, 1, 0); PG8_STAGE(PG8_SA(0, 1), a2 + hstepA, voffA);
;             PG8_WAIT_V(8); PG8_WAIT_L(0); PG8_BAR; PG8_MMA(0, 0, At, B0); PG8_MMA(0, 1, At, B1); PG8_BAR; PG8_SCHED;
	s_setprio 1
	v_mfma_f32_16x16x32_bf16 v[60:63], v[64:67], v[160:163], v[60:63]
	v_mfma_f32_16x16x32_bf16 v[56:59], v[80:83], v[160:163], v[56:59]
	v_mfma_f32_16x16x32_bf16 v[44:47], v[64:67], v[168:171], v[44:47]
	v_mfma_f32_16x16x32_bf16 v[40:43], v[80:83], v[168:171], v[40:43]
	v_mfma_f32_16x16x32_bf16 v[28:31], v[64:67], v[176:179], v[28:31]
	v_mfma_f32_16x16x32_bf16 v[24:27], v[80:83], v[176:179], v[24:27]
	v_mfma_f32_16x16x32_bf16 v[12:15], v[64:67], v[184:187], v[12:15]
	v_mfma_f32_16x16x32_bf16 v[8:11], v[80:83], v[184:187], v[8:11]
	v_mfma_f32_16x16x32_bf16 v[60:63], v[76:79], v[164:167], v[60:63]
	v_mfma_f32_16x16x32_bf16 v[56:59], v[92:95], v[164:167], v[56:59]
	v_mfma_f32_16x16x32_bf16 v[44:47], v[76:79], v[172:175], v[44:47]
	v_mfma_f32_16x16x32_bf16 v[40:43], v[92:95], v[172:175], v[40:43]
	v_mfma_f32_16x16x32_bf16 v[28:31], v[76:79], v[180:183], v[28:31]
	v_mfma_f32_16x16x32_bf16 v[24:27], v[92:95], v[180:183], v[24:27]
	v_mfma_f32_16x16x32_bf16 v[12:15], v[76:79], v[188:191], v[12:15]
	v_mfma_f32_16x16x32_bf16 v[8:11], v[92:95], v[188:191], v[8:11]
	s_setprio 0
	s_setprio 1
	v_mfma_f32_16x16x32_bf16 v[52:55], v[104:107], v[160:163], v[52:55]
	v_mfma_f32_16x16x32_bf16 v[48:51], v[128:131], v[160:163], v[48:51]
	v_mfma_f32_16x16x32_bf16 v[36:39], v[104:107], v[168:171], v[36:39]
	v_mfma_f32_16x16x32_bf16 v[32:35], v[128:131], v[168:171], v[32:35]
	v_mfma_f32_16x16x32_bf16 v[20:23], v[104:107], v[176:179], v[20:23]
	v_mfma_f32_16x16x32_bf16 v[16:19], v[128:131], v[176:179], v[16:19]
	v_mfma_f32_16x16x32_bf16 v[4:7], v[104:107], v[184:187], v[4:7]
	v_mfma_f32_16x16x32_bf16 v[0:3], v[128:131], v[184:187], v[0:3]
	v_mfma_f32_16x16x32_bf16 v[52:55], v[116:119], v[164:167], v[52:55]
	v_mfma_f32_16x16x32_bf16 v[48:51], v[132:135], v[164:167], v[48:51]
	v_mfma_f32_16x16x32_bf16 v[36:39], v[116:119], v[172:175], v[36:39]
	v_mfma_f32_16x16x32_bf16 v[32:35], v[132:135], v[172:175], v[32:35]
	v_mfma_f32_16x16x32_bf16 v[20:23], v[116:119], v[180:183], v[20:23]
	v_mfma_f32_16x16x32_bf16 v[16:19], v[132:135], v[180:183], v[16:19]
	v_mfma_f32_16x16x32_bf16 v[4:7], v[116:119], v[188:191], v[4:7]
	v_mfma_f32_16x16x32_bf16 v[0:3], v[132:135], v[188:191], v[0:3]
	s_setprio 0
	s_barrier
	s_add_i32 s25, 0, 0x18000
	s_add_i32 s56, 0, 0x1c000
	v_add_u32_e32 v92, s25, v237
	v_add_u32_e32 v132, s56, v237
	ds_read_b128 v[64:67], v92
	ds_read_b128 v[76:79], v92 offset:1024
	ds_read_b128 v[80:83], v92 offset:2048
	ds_read_b128 v[92:95], v92 offset:3072
	ds_read_b128 v[104:107], v132
	ds_read_b128 v[116:119], v132 offset:1024
	ds_read_b128 v[128:131], v132 offset:2048
	ds_read_b128 v[132:135], v132 offset:3072
	s_add_u32 s68, s88, 0x20000
	s_addc_u32 s69, s89, 0
	s_mov_b32 m0, s39
	v_lshl_add_u64 v[218:219], s[68:69], 0, v[200:201]
	ds_read_b128 v[160:163], v239 offset:32768
	ds_read_b128 v[164:167], v239 offset:33792
	ds_read_b128 v[168:171], v239 offset:34816
	ds_read_b128 v[172:175], v239 offset:35840
	ds_read_b128 v[176:179], v239 offset:36864
	ds_read_b128 v[180:183], v239 offset:37888
	ds_read_b128 v[184:187], v239 offset:38912
	ds_read_b128 v[188:191], v239 offset:39936
	global_load_lds_dwordx4 v[218:219], off
	v_lshl_add_u64 v[218:219], s[68:69], 0, v[202:203]
	s_mov_b32 m0, s28
	s_nop 0
	global_load_lds_dwordx4 v[218:219], off
	s_waitcnt vmcnt(8) lgkmcnt(0)
	s_barrier
	s_setprio 1
	v_mfma_f32_16x16x32_bf16 v[156:159], v[64:67], v[160:163], v[156:159]
	v_mfma_f32_16x16x32_bf16 v[152:155], v[80:83], v[160:163], v[152:155]
	v_mfma_f32_16x16x32_bf16 v[140:143], v[64:67], v[168:171], v[140:143]
	v_mfma_f32_16x16x32_bf16 v[136:139], v[80:83], v[168:171], v[136:139]
	v_mfma_f32_16x16x32_bf16 v[112:115], v[64:67], v[176:179], v[112:115]
	v_mfma_f32_16x16x32_bf16 v[108:111], v[80:83], v[176:179], v[108:111]
	v_mfma_f32_16x16x32_bf16 v[88:91], v[64:67], v[184:187], v[88:91]
	v_mfma_f32_16x16x32_bf16 v[84:87], v[80:83], v[184:187], v[84:87]
	v_mfma_f32_16x16x32_bf16 v[156:159], v[76:79], v[164:167], v[156:159]
	v_mfma_f32_16x16x32_bf16 v[152:155], v[92:95], v[164:167], v[152:155]
	v_mfma_f32_16x16x32_bf16 v[140:143], v[76:79], v[172:175], v[140:143]
	v_mfma_f32_16x16x32_bf16 v[136:139], v[92:95], v[172:175], v[136:139]
	v_mfma_f32_16x16x32_bf16 v[112:115], v[76:79], v[180:183], v[112:115]
	v_mfma_f32_16x16x32_bf16 v[108:111], v[92:95], v[180:183], v[108:111]
	v_mfma_f32_16x16x32_bf16 v[88:91], v[76:79], v[188:191], v[88:91]
	v_mfma_f32_16x16x32_bf16 v[84:87], v[92:95], v[188:191], v[84:87]
	s_setprio 0
	s_setprio 1
	v_mfma_f32_16x16x32_bf16 v[148:151], v[104:107], v[160:163], v[148:151]
	v_mfma_f32_16x16x32_bf16 v[144:147], v[128:131], v[160:163], v[144:147]
	v_mfma_f32_16x16x32_bf16 v[124:127], v[104:107], v[168:171], v[124:127]
	v_mfma_f32_16x16x32_bf16 v[120:123], v[128:131], v[168:171], v[120:123]
	v_mfma_f32_16x16x32_bf16 v[100:103], v[104:107], v[176:179], v[100:103]
	v_mfma_f32_16x16x32_bf16 v[96:99], v[128:131], v[176:179], v[96:99]
	v_mfma_f32_16x16x32_bf16 v[72:75], v[104:107], v[184:187], v[72:75]
	v_mfma_f32_16x16x32_bf16 v[68:71], v[128:131], v[184:187], v[68:71]
	v_mfma_f32_16x16x32_bf16 v[148:151], v[116:119], v[164:167], v[148:151]
	v_mfma_f32_16x16x32_bf16 v[144:147], v[132:135], v[164:167], v[144:147]
	v_mfma_f32_16x16x32_bf16 v[124:127], v[116:119], v[172:175], v[124:127]
	v_mfma_f32_16x16x32_bf16 v[120:123], v[132:135], v[172:175], v[120:123]
	v_mfma_f32_16x16x32_bf16 v[100:103], v[116:119], v[180:183], v[100:103]
	v_mfma_f32_16x16x32_bf16 v[96:99], v[132:135], v[180:183], v[96:99]
	v_mfma_f32_16x16x32_bf16 v[72:75], v[116:119], v[188:191], v[72:75]
	v_mfma_f32_16x16x32_bf16 v[68:71], v[132:135], v[188:191], v[68:71]
	s_setprio 0
	s_barrier
; #define PG8_STAGE(bufoff, gbase, voff) do { _Pragma("unroll") for (int _i = 0; _i < 2; ++_i) \
;         __builtin_amdgcn_global_load_lds((const unsigned*)((const char*)(gbase) + (voff)[_i]), (PG8_LAS unsigned*)(lds + (bufoff) + ldsw + _i * 8192), 16, 0, 0); } while (0)
; #define PG8_LDA(dst, b, h) do { _Pragma("unroll") for (int m = 0; m < 4; ++m) _Pragma("unroll") for (int k = 0; k < 2; ++k) dst[m][k] = *(const PG8_LAS bf16x8*)(lds + PG8_SA(b, h) + aoff + m * 2048 + k * 1024); } while (0)
; #define PG8_MMA(ai, bj, At, Bt) do { __builtin_amdgcn_s_setprio(1); _Pragma("unroll") for (int m = 0; m < 4; ++m) _Pragma("unroll") for (int n = 0; n < 2; ++n) _Pragma("unroll") for (int k = 0; k < 2; ++k) \
;         acc[ai][bj][m][n] = __builtin_amdgcn_mfma_f32_16x16x32_bf16(Bt[n][k], At[m][k], acc[ai][bj][m][n], 0, 0, 0); __builtin_amdgcn_s_setprio(0); } while (0)
; #define PG8_WAIT_V(n) asm volatile("s_waitcnt vmcnt(" #n ")" ::: "memory")
; #define PG8_WAIT_L(n) asm volatile("s_waitcnt lgkmcnt(" #n ")" ::: "memory")
; #define PG8_BAR __builtin_amdgcn_s_barrier()
; #define PG8_SCHED __builtin_amdgcn_sched_barrier(0)
; template <class Epi, class Sched, bool ALIGN_EPI = false, bool SP2 = false>
; __device__ __forceinline__ void gemm_phase(PG8_LAS unsigned char* lds, const Gemm g, const Sched& S, const Epi& E, const int tid) {
;     ...
;             PG8_LDA(At, 1, 1); PG8_STAGE(PG8_SB(1, 0), b3, voffB); PG8_STAGE(PG8_SB(1, 1), b3 + hstepB, voffB); PG8_STAGE(PG8_SA(1, 0), a3, voffA);
;             PG8_WAIT_V(8); PG8_WAIT_L(0); PG8_BAR; PG8_MMA(1, 0, At, B0); PG8_MMA(1, 1, At, B1); PG8_BAR; PG8_SCHED;
;     ...
;         if constexpr (ALIGN_EPI) { if (wr == 0) PG8_BAR; }
	s_add_i32 s25, s25, s16
	v_lshl_add_u64 v[210:211], v[210:211], 0, s[60:61]
	s_mov_b32 m0, s25
	ds_read_b128 v[160:163], v239 offset:49152
	ds_read_b128 v[164:167], v239 offset:50176
	ds_read_b128 v[168:171], v239 offset:51200
	ds_read_b128 v[172:175], v239 offset:52224
	ds_read_b128 v[176:179], v239 offset:53248
	ds_read_b128 v[180:183], v239 offset:54272
	ds_read_b128 v[184:187], v239 offset:55296
	ds_read_b128 v[188:191], v239 offset:56320
	global_load_lds_dwordx4 v[210:211], off
	s_add_i32 m0, s25, 0x2000
	s_add_u32 s68, s86, 0x20080
	v_lshl_add_u64 v[210:211], v[212:213], 0, s[60:61]
	s_addc_u32 s69, s87, 0
	s_add_i32 s25, s56, s16
	global_load_lds_dwordx4 v[210:211], off
	v_lshl_add_u64 v[210:211], s[68:69], 0, v[192:193]
	s_mov_b32 m0, s25
	s_nop 0
	global_load_lds_dwordx4 v[210:211], off
	v_lshl_add_u64 v[210:211], s[68:69], 0, v[204:205]
	s_add_i32 m0, s25, 0x2000
	s_nop 0
	global_load_lds_dwordx4 v[210:211], off
	v_lshl_add_u64 v[210:211], v[214:215], 0, s[60:61]
	s_mov_b32 m0, s29
	s_nop 0
	global_load_lds_dwordx4 v[210:211], off
	v_lshl_add_u64 v[210:211], v[216:217], 0, s[60:61]
	s_mov_b32 m0, s14
	s_nop 0
	global_load_lds_dwordx4 v[210:211], off
	s_waitcnt vmcnt(8) lgkmcnt(0)
	s_barrier
	s_setprio 1
	v_mfma_f32_16x16x32_bf16 v[60:63], v[64:67], v[160:163], v[60:63]
	v_mfma_f32_16x16x32_bf16 v[56:59], v[80:83], v[160:163], v[56:59]
	v_mfma_f32_16x16x32_bf16 v[44:47], v[64:67], v[168:171], v[44:47]
	v_mfma_f32_16x16x32_bf16 v[40:43], v[80:83], v[168:171], v[40:43]
	v_mfma_f32_16x16x32_bf16 v[28:31], v[64:67], v[176:179], v[28:31]
	v_mfma_f32_16x16x32_bf16 v[24:27], v[80:83], v[176:179], v[24:27]
	v_mfma_f32_16x16x32_bf16 v[12:15], v[64:67], v[184:187], v[12:15]
	v_mfma_f32_16x16x32_bf16 v[8:11], v[80:83], v[184:187], v[8:11]
	v_mfma_f32_16x16x32_bf16 v[60:63], v[76:79], v[164:167], v[60:63]
	v_mfma_f32_16x16x32_bf16 v[56:59], v[92:95], v[164:167], v[56:59]
	v_mfma_f32_16x16x32_bf16 v[44:47], v[76:79], v[172:175], v[44:47]
	v_mfma_f32_16x16x32_bf16 v[40:43], v[92:95], v[172:175], v[40:43]
	v_mfma_f32_16x16x32_bf16 v[28:31], v[76:79], v[180:183], v[28:31]
	v_mfma_f32_16x16x32_bf16 v[24:27], v[92:95], v[180:183], v[24:27]
	v_mfma_f32_16x16x32_bf16 v[12:15], v[76:79], v[188:191], v[12:15]
	v_mfma_f32_16x16x32_bf16 v[8:11], v[92:95], v[188:191], v[8:11]
	s_setprio 0
	s_setprio 1
	v_mfma_f32_16x16x32_bf16 v[52:55], v[104:107], v[160:163], v[52:55]
	v_mfma_f32_16x16x32_bf16 v[48:51], v[128:131], v[160:163], v[48:51]
	v_mfma_f32_16x16x32_bf16 v[36:39], v[104:107], v[168:171], v[36:39]
	v_mfma_f32_16x16x32_bf16 v[32:35], v[128:131], v[168:171], v[32:35]
	v_mfma_f32_16x16x32_bf16 v[20:23], v[104:107], v[176:179], v[20:23]
	v_mfma_f32_16x16x32_bf16 v[16:19], v[128:131], v[176:179], v[16:19]
	v_mfma_f32_16x16x32_bf16 v[4:7], v[104:107], v[184:187], v[4:7]
	v_mfma_f32_16x16x32_bf16 v[0:3], v[128:131], v[184:187], v[0:3]
	v_mfma_f32_16x16x32_bf16 v[52:55], v[116:119], v[164:167], v[52:55]
	v_mfma_f32_16x16x32_bf16 v[48:51], v[132:135], v[164:167], v[48:51]
	v_mfma_f32_16x16x32_bf16 v[36:39], v[116:119], v[172:175], v[36:39]
	v_mfma_f32_16x16x32_bf16 v[32:35], v[132:135], v[172:175], v[32:35]
	v_mfma_f32_16x16x32_bf16 v[20:23], v[116:119], v[180:183], v[20:23]
	v_mfma_f32_16x16x32_bf16 v[16:19], v[132:135], v[180:183], v[16:19]
	v_mfma_f32_16x16x32_bf16 v[4:7], v[116:119], v[188:191], v[4:7]
	v_mfma_f32_16x16x32_bf16 v[0:3], v[132:135], v[188:191], v[0:3]
	s_setprio 0
	s_barrier
	s_add_i32 s24, s24, 2
	s_add_u32 s2, s2, 0x100
	s_addc_u32 s74, s74, 0
	s_add_u32 s6, s6, 0x100
	s_addc_u32 s7, s7, 0
	s_cmp_gt_u32 s24, 5
	s_cbranch_scc0 .LBB0_90
	s_and_b64 vcc, exec, s[48:49]
	s_cbranch_vccz .LBB0_93
	s_barrier

; #define PG8_STAGE(bufoff, gbase, voff) do { _Pragma("unroll") for (int _i = 0; _i < 2; ++_i) \
;         __builtin_amdgcn_global_load_lds((const unsigned*)((const char*)(gbase) + (voff)[_i]), (PG8_LAS unsigned*)(lds + (bufoff) + ldsw + _i * 8192), 16, 0, 0); } while (0)
; #define PG8_LDA(dst, b, h) do { _Pragma("unroll") for (int m = 0; m < 4; ++m) _Pragma("unroll") for (int k = 0; k < 2; ++k) dst[m][k] = *(const PG8_LAS bf16x8*)(lds + PG8_SA(b, h) + aoff + m * 2048 + k * 1024); } while (0)
; #define PG8_LDB(dst, b, h) do { _Pragma("unroll") for (int n = 0; n < 2; ++n) _Pragma("unroll") for (int k = 0; k < 2; ++k) dst[n][k] = *(const PG8_LAS bf16x8*)(lds + PG8_SB(b, h) + boff + n * 2048 + k * 1024); } while (0)
; #define PG8_MMA(ai, bj, At, Bt) do { __builtin_amdgcn_s_setprio(1); _Pragma("unroll") for (int m = 0; m < 4; ++m) _Pragma("unroll") for (int n = 0; n < 2; ++n) _Pragma("unroll") for (int k = 0; k < 2; ++k) \
;         acc[ai][bj][m][n] = __builtin_amdgcn_mfma_f32_16x16x32_bf16(Bt[n][k], At[m][k], acc[ai][bj][m][n], 0, 0, 0); __builtin_amdgcn_s_setprio(0); } while (0)
; #define PG8_WAIT_V(n) asm volatile("s_waitcnt vmcnt(" #n ")" ::: "memory")
; #define PG8_WAIT_L(n) asm volatile("s_waitcnt lgkmcnt(" #n ")" ::: "memory")
; template <class Epi, class Sched, bool ALIGN_EPI = false, bool SP2 = false>
; __device__ __forceinline__ void gemm_phase(PG8_LAS unsigned char* lds, const Gemm g, const Sched& S, const Epi& E, const int tid) {
;     ...
;             const bool last = (t == nt - 2);
;             const char* a1 = cA + (size_t)(t + 1) * kstep;
;             const char* a2 = last ? nA : cA + (size_t)(t + 2) * kstep; const char* b2 = last ? nB : cB + (size_t)(t + 2) * kstep;
;             const char* a3 = a2 + kstep; const char* b3 = b2 + kstep;
;             if (last && has_next) S.a_ready(nxt);
;             if constexpr (SP2) {
;             PG8_LDB(B0, 0, 0); PG8_LDB(B1, 0, 1); PG8_SCHED; PG8_LDA(At, 0, 0); PG8_STAGE(PG8_SA(1, 1), a1 + hstepA, voffA);
;             PG8_WAIT_V(8); PG8_WAIT_L(0); PG8_BAR; PG8_MMA(0, 0, At, B0); PG8_MMA(0, 1, At, B1); PG8_BAR; PG8_SCHED;
;             PG8_LDA(At, 0, 1); PG8_STAGE(PG8_SB(0, 0), b2, voffB); PG8_STAGE(PG8_SB(0, 1), b2 + hstepB, voffB); PG8_STAGE(PG8_SA(0, 0), a2, voffA);
;             PG8_WAIT_V(8); PG8_WAIT_L(0); PG8_BAR; PG8_MMA(1, 0, At, B0); PG8_MMA(1, 1, At, B1); PG8_BAR; PG8_SCHED;
.LBB0_248:
	s_add_i32 vcc_lo, s52, 2
	s_add_u32 s50, s48, 0x100
	s_addc_u32 s51, s49, 0
	s_add_i32 s68, 0, 0x10000
	s_cmp_eq_u32 s87, s52
	s_cselect_b32 s53, s45, s51
	s_cselect_b32 s52, s44, s50
	v_add_u32_e32 v142, s68, v155
	s_cselect_b32 s43, s47, s25
	s_cselect_b32 s42, s46, s24
	s_add_i32 s69, 0, 0x14000
	ds_read_b128 v[138:141], v142
	ds_read_b128 v[158:161], v142 offset:1024
	ds_read_b128 v[162:165], v142 offset:2048
	ds_read_b128 v[166:169], v142 offset:3072
	v_add_u32_e32 v142, s69, v155
	ds_read_b128 v[170:173], v142
	ds_read_b128 v[174:177], v142 offset:1024
	ds_read_b128 v[178:181], v142 offset:2048
	ds_read_b128 v[182:185], v142 offset:3072
	v_lshl_add_u64 v[142:143], s[48:49], 0, v[134:135]
	s_add_i32 m0, s79, 0xc000
	ds_read_b128 v[186:189], v157
	ds_read_b128 v[200:203], v157 offset:1024
	ds_read_b128 v[204:207], v157 offset:2048
	ds_read_b128 v[208:211], v157 offset:3072
	ds_read_b128 v[212:215], v157 offset:4096
	ds_read_b128 v[216:219], v157 offset:5120
	ds_read_b128 v[220:223], v157 offset:6144
	ds_read_b128 v[234:237], v157 offset:7168
	global_load_lds_dwordx4 v[142:143], off
	v_lshl_add_u64 v[142:143], s[48:49], 0, v[132:133]
	s_add_i32 m0, s79, 0xe000
	s_nop 0
	global_load_lds_dwordx4 v[142:143], off
	s_waitcnt vmcnt(8) lgkmcnt(0)
	s_barrier
	s_setprio 1
	v_mfma_f32_16x16x32_bf16 v[124:127], v[138:141], v[186:189], v[124:127]
	v_mfma_f32_16x16x32_bf16 v[120:123], v[162:165], v[186:189], v[120:123]
	v_mfma_f32_16x16x32_bf16 v[108:111], v[138:141], v[204:207], v[108:111]
	v_mfma_f32_16x16x32_bf16 v[104:107], v[162:165], v[204:207], v[104:107]
	v_mfma_f32_16x16x32_bf16 v[92:95], v[138:141], v[212:215], v[92:95]
	v_mfma_f32_16x16x32_bf16 v[88:91], v[162:165], v[212:215], v[88:91]
	v_mfma_f32_16x16x32_bf16 v[76:79], v[138:141], v[220:223], v[76:79]
	v_mfma_f32_16x16x32_bf16 v[72:75], v[162:165], v[220:223], v[72:75]
	v_mfma_f32_16x16x32_bf16 v[124:127], v[158:161], v[200:203], v[124:127]
	v_mfma_f32_16x16x32_bf16 v[120:123], v[166:169], v[200:203], v[120:123]
	v_mfma_f32_16x16x32_bf16 v[108:111], v[158:161], v[208:211], v[108:111]
	v_mfma_f32_16x16x32_bf16 v[104:107], v[166:169], v[208:211], v[104:107]
	v_mfma_f32_16x16x32_bf16 v[92:95], v[158:161], v[216:219], v[92:95]
	v_mfma_f32_16x16x32_bf16 v[88:91], v[166:169], v[216:219], v[88:91]
	v_mfma_f32_16x16x32_bf16 v[76:79], v[158:161], v[234:237], v[76:79]
	v_mfma_f32_16x16x32_bf16 v[72:75], v[166:169], v[234:237], v[72:75]
	s_setprio 0
	s_setprio 1
	v_mfma_f32_16x16x32_bf16 v[116:119], v[170:173], v[186:189], v[116:119]
	v_mfma_f32_16x16x32_bf16 v[112:115], v[178:181], v[186:189], v[112:115]
	v_mfma_f32_16x16x32_bf16 v[100:103], v[170:173], v[204:207], v[100:103]
	v_mfma_f32_16x16x32_bf16 v[96:99], v[178:181], v[204:207], v[96:99]
	v_mfma_f32_16x16x32_bf16 v[84:87], v[170:173], v[212:215], v[84:87]
	v_mfma_f32_16x16x32_bf16 v[80:83], v[178:181], v[212:215], v[80:83]
	v_mfma_f32_16x16x32_bf16 v[68:71], v[170:173], v[220:223], v[68:71]
	v_mfma_f32_16x16x32_bf16 v[64:67], v[178:181], v[220:223], v[64:67]
	v_mfma_f32_16x16x32_bf16 v[116:119], v[174:177], v[200:203], v[116:119]
	v_mfma_f32_16x16x32_bf16 v[112:115], v[182:185], v[200:203], v[112:115]
	v_mfma_f32_16x16x32_bf16 v[100:103], v[174:177], v[208:211], v[100:103]
	v_mfma_f32_16x16x32_bf16 v[96:99], v[182:185], v[208:211], v[96:99]
	v_mfma_f32_16x16x32_bf16 v[84:87], v[174:177], v[216:219], v[84:87]
	v_mfma_f32_16x16x32_bf16 v[80:83], v[182:185], v[216:219], v[80:83]
	v_mfma_f32_16x16x32_bf16 v[68:71], v[174:177], v[234:237], v[68:71]
	v_mfma_f32_16x16x32_bf16 v[64:67], v[182:185], v[234:237], v[64:67]
	s_setprio 0
	s_barrier
	s_add_i32 s48, s68, s65
	v_lshl_add_u64 v[142:143], s[42:43], 0, v[192:193]
	s_mov_b32 m0, s48
	ds_read_b128 v[186:189], v157 offset:16384
	ds_read_b128 v[200:203], v157 offset:17408
	ds_read_b128 v[204:207], v157 offset:18432
	ds_read_b128 v[208:211], v157 offset:19456
	ds_read_b128 v[212:215], v157 offset:20480
	ds_read_b128 v[216:219], v157 offset:21504
	ds_read_b128 v[220:223], v157 offset:22528
	ds_read_b128 v[234:237], v157 offset:23552
	global_load_lds_dwordx4 v[142:143], off
	s_add_i32 m0, s48, 0x2000
	v_lshl_add_u64 v[190:191], s[42:43], 0, v[136:137]
	s_add_u32 s42, s42, s55
	s_addc_u32 s43, s43, 0
	s_add_i32 s48, s69, s65
	global_load_lds_dwordx4 v[190:191], off
	v_lshl_add_u64 v[238:239], s[42:43], 0, v[192:193]
	s_mov_b32 m0, s48
	v_lshl_add_u64 v[240:241], s[42:43], 0, v[136:137]
	global_load_lds_dwordx4 v[238:239], off
	s_add_i32 m0, s48, 0x2000
	v_lshl_add_u64 v[242:243], s[52:53], 0, v[130:131]
	global_load_lds_dwordx4 v[240:241], off
	s_mov_b32 m0, s79
	v_lshl_add_u64 v[244:245], s[52:53], 0, v[128:129]
	global_load_lds_dwordx4 v[242:243], off
	s_mov_b32 m0, s80
	s_nop 0
	global_load_lds_dwordx4 v[244:245], off
	s_waitcnt vmcnt(8) lgkmcnt(0)
	s_barrier
; #define PG8_STAGE(bufoff, gbase, voff) do { _Pragma("unroll") for (int _i = 0; _i < 2; ++_i) \
;         __builtin_amdgcn_global_load_lds((const unsigned*)((const char*)(gbase) + (voff)[_i]), (PG8_LAS unsigned*)(lds + (bufoff) + ldsw + _i * 8192), 16, 0, 0); } while (0)
; #define PG8_LDA(dst, b, h) do { _Pragma("unroll") for (int m = 0; m < 4; ++m) _Pragma("unroll") for (int k = 0; k < 2; ++k) dst[m][k] = *(const PG8_LAS bf16x8*)(lds + PG8_SA(b, h) + aoff + m * 2048 + k * 1024); } while (0)
; #define PG8_LDB(dst, b, h) do { _Pragma("unroll") for (int n = 0; n < 2; ++n) _Pragma("unroll") for (int k = 0; k < 2; ++k) dst[n][k] = *(const PG8_LAS bf16x8*)(lds + PG8_SB(b, h) + boff + n * 2048 + k * 1024); } while (0)
; #define PG8_MMA(ai, bj, At, Bt) do { __builtin_amdgcn_s_setprio(1); _Pragma("unroll") for (int m = 0; m < 4; ++m) _Pragma("unroll") for (int n = 0; n < 2; ++n) _Pragma("unroll") for (int k = 0; k < 2; ++k) \
;         acc[ai][bj][m][n] = __builtin_amdgcn_mfma_f32_16x16x32_bf16(Bt[n][k], At[m][k], acc[ai][bj][m][n], 0, 0, 0); __builtin_amdgcn_s_setprio(0); } while (0)
; #define PG8_WAIT_V(n) asm volatile("s_waitcnt vmcnt(" #n ")" ::: "memory")
; #define PG8_WAIT_L(n) asm volatile("s_waitcnt lgkmcnt(" #n ")" ::: "memory")
; #define PG8_BAR __builtin_amdgcn_s_barrier()
; #define PG8_SCHED __builtin_amdgcn_sched_barrier(0)
; template <class Epi, class Sched, bool ALIGN_EPI = false, bool SP2 = false>
; __device__ __forceinline__ void gemm_phase(PG8_LAS unsigned char* lds, const Gemm g, const Sched& S, const Epi& E, const int tid) {
;     ...
;             PG8_WAIT_V(8); PG8_WAIT_L(0); PG8_BAR; PG8_MMA(1, 0, At, B0); PG8_MMA(1, 1, At, B1); PG8_BAR; PG8_SCHED;
;             PG8_LDB(B0, 1, 0); PG8_LDB(B1, 1, 1); PG8_SCHED; PG8_LDA(At, 1, 0); PG8_STAGE(PG8_SA(0, 1), a2 + hstepA, voffA);
;             PG8_WAIT_V(8); PG8_WAIT_L(0); PG8_BAR; PG8_MMA(0, 0, At, B0); PG8_MMA(0, 1, At, B1); PG8_BAR; PG8_SCHED;
	s_setprio 1
	v_mfma_f32_16x16x32_bf16 v[60:63], v[138:141], v[186:189], v[60:63]
	v_mfma_f32_16x16x32_bf16 v[56:59], v[162:165], v[186:189], v[56:59]
	v_mfma_f32_16x16x32_bf16 v[44:47], v[138:141], v[204:207], v[44:47]
	v_mfma_f32_16x16x32_bf16 v[40:43], v[162:165], v[204:207], v[40:43]
	v_mfma_f32_16x16x32_bf16 v[28:31], v[138:141], v[212:215], v[28:31]
	v_mfma_f32_16x16x32_bf16 v[24:27], v[162:165], v[212:215], v[24:27]
	v_mfma_f32_16x16x32_bf16 v[12:15], v[138:141], v[220:223], v[12:15]
	v_mfma_f32_16x16x32_bf16 v[8:11], v[162:165], v[220:223], v[8:11]
	v_mfma_f32_16x16x32_bf16 v[60:63], v[158:161], v[200:203], v[60:63]
	v_mfma_f32_16x16x32_bf16 v[56:59], v[166:169], v[200:203], v[56:59]
	v_mfma_f32_16x16x32_bf16 v[44:47], v[158:161], v[208:211], v[44:47]
	v_mfma_f32_16x16x32_bf16 v[40:43], v[166:169], v[208:211], v[40:43]
	v_mfma_f32_16x16x32_bf16 v[28:31], v[158:161], v[216:219], v[28:31]
	v_mfma_f32_16x16x32_bf16 v[24:27], v[166:169], v[216:219], v[24:27]
	v_mfma_f32_16x16x32_bf16 v[12:15], v[158:161], v[234:237], v[12:15]
	v_mfma_f32_16x16x32_bf16 v[8:11], v[166:169], v[234:237], v[8:11]
	s_setprio 0
	s_setprio 1
	v_mfma_f32_16x16x32_bf16 v[52:55], v[170:173], v[186:189], v[52:55]
	v_mfma_f32_16x16x32_bf16 v[48:51], v[178:181], v[186:189], v[48:51]
	v_mfma_f32_16x16x32_bf16 v[36:39], v[170:173], v[204:207], v[36:39]
	v_mfma_f32_16x16x32_bf16 v[32:35], v[178:181], v[204:207], v[32:35]
	v_mfma_f32_16x16x32_bf16 v[20:23], v[170:173], v[212:215], v[20:23]
	v_mfma_f32_16x16x32_bf16 v[16:19], v[178:181], v[212:215], v[16:19]
	v_mfma_f32_16x16x32_bf16 v[4:7], v[170:173], v[220:223], v[4:7]
	v_mfma_f32_16x16x32_bf16 v[0:3], v[178:181], v[220:223], v[0:3]
	v_mfma_f32_16x16x32_bf16 v[52:55], v[174:177], v[200:203], v[52:55]
	v_mfma_f32_16x16x32_bf16 v[48:51], v[182:185], v[200:203], v[48:51]
	v_mfma_f32_16x16x32_bf16 v[36:39], v[174:177], v[208:211], v[36:39]
	v_mfma_f32_16x16x32_bf16 v[32:35], v[182:185], v[208:211], v[32:35]
	v_mfma_f32_16x16x32_bf16 v[20:23], v[174:177], v[216:219], v[20:23]
	v_mfma_f32_16x16x32_bf16 v[16:19], v[182:185], v[216:219], v[16:19]
	v_mfma_f32_16x16x32_bf16 v[4:7], v[174:177], v[234:237], v[4:7]
	v_mfma_f32_16x16x32_bf16 v[0:3], v[182:185], v[234:237], v[0:3]
	s_setprio 0
	s_barrier
	s_add_i32 s48, 0, 0x18000
	v_add_u32_e32 v144, s48, v155
	s_add_i32 s49, 0, 0x1c000
	ds_read_b128 v[138:141], v144
	ds_read_b128 v[158:161], v144 offset:1024
	ds_read_b128 v[162:165], v144 offset:2048
	ds_read_b128 v[166:169], v144 offset:3072
	v_add_u32_e32 v144, s49, v155
	ds_read_b128 v[170:173], v144
	ds_read_b128 v[174:177], v144 offset:1024
	ds_read_b128 v[178:181], v144 offset:2048
	ds_read_b128 v[182:185], v144 offset:3072
	s_add_u32 s42, s52, 0x30000
	s_addc_u32 s43, s53, 0
	s_mov_b32 m0, s81
	v_lshl_add_u64 v[246:247], s[42:43], 0, v[130:131]
	ds_read_b128 v[186:189], v157 offset:32768
	ds_read_b128 v[200:203], v157 offset:33792
	ds_read_b128 v[204:207], v157 offset:34816
	ds_read_b128 v[208:211], v157 offset:35840
	ds_read_b128 v[212:215], v157 offset:36864
	ds_read_b128 v[216:219], v157 offset:37888
	ds_read_b128 v[220:223], v157 offset:38912
	ds_read_b128 v[234:237], v157 offset:39936
	global_load_lds_dwordx4 v[246:247], off
	v_lshl_add_u64 v[246:247], s[42:43], 0, v[128:129]
	s_mov_b32 m0, s82
	s_nop 0
	global_load_lds_dwordx4 v[246:247], off
	s_waitcnt vmcnt(8) lgkmcnt(0)
	s_barrier
	s_setprio 1
	v_mfma_f32_16x16x32_bf16 v[124:127], v[138:141], v[186:189], v[124:127]
	v_mfma_f32_16x16x32_bf16 v[120:123], v[162:165], v[186:189], v[120:123]
	v_mfma_f32_16x16x32_bf16 v[108:111], v[138:141], v[204:207], v[108:111]
	v_mfma_f32_16x16x32_bf16 v[104:107], v[162:165], v[204:207], v[104:107]
	v_mfma_f32_16x16x32_bf16 v[92:95], v[138:141], v[212:215], v[92:95]
	v_mfma_f32_16x16x32_bf16 v[88:91], v[162:165], v[212:215], v[88:91]
	v_mfma_f32_16x16x32_bf16 v[76:79], v[138:141], v[220:223], v[76:79]
	v_mfma_f32_16x16x32_bf16 v[72:75], v[162:165], v[220:223], v[72:75]
	v_mfma_f32_16x16x32_bf16 v[124:127], v[158:161], v[200:203], v[124:127]
	v_mfma_f32_16x16x32_bf16 v[120:123], v[166:169], v[200:203], v[120:123]
	v_mfma_f32_16x16x32_bf16 v[108:111], v[158:161], v[208:211], v[108:111]
	v_mfma_f32_16x16x32_bf16 v[104:107], v[166:169], v[208:211], v[104:107]
	v_mfma_f32_16x16x32_bf16 v[92:95], v[158:161], v[216:219], v[92:95]
	v_mfma_f32_16x16x32_bf16 v[88:91], v[166:169], v[216:219], v[88:91]
	v_mfma_f32_16x16x32_bf16 v[76:79], v[158:161], v[234:237], v[76:79]
	v_mfma_f32_16x16x32_bf16 v[72:75], v[166:169], v[234:237], v[72:75]
	s_setprio 0
	s_setprio 1
	v_mfma_f32_16x16x32_bf16 v[116:119], v[170:173], v[186:189], v[116:119]
	v_mfma_f32_16x16x32_bf16 v[112:115], v[178:181], v[186:189], v[112:115]
	v_mfma_f32_16x16x32_bf16 v[100:103], v[170:173], v[204:207], v[100:103]
	v_mfma_f32_16x16x32_bf16 v[96:99], v[178:181], v[204:207], v[96:99]
	v_mfma_f32_16x16x32_bf16 v[84:87], v[170:173], v[212:215], v[84:87]
	v_mfma_f32_16x16x32_bf16 v[80:83], v[178:181], v[212:215], v[80:83]
	v_mfma_f32_16x16x32_bf16 v[68:71], v[170:173], v[220:223], v[68:71]
	v_mfma_f32_16x16x32_bf16 v[64:67], v[178:181], v[220:223], v[64:67]
	v_mfma_f32_16x16x32_bf16 v[116:119], v[174:177], v[200:203], v[116:119]
	v_mfma_f32_16x16x32_bf16 v[112:115], v[182:185], v[200:203], v[112:115]
	v_mfma_f32_16x16x32_bf16 v[100:103], v[174:177], v[208:211], v[100:103]
	v_mfma_f32_16x16x32_bf16 v[96:99], v[182:185], v[208:211], v[96:99]
	v_mfma_f32_16x16x32_bf16 v[84:87], v[174:177], v[216:219], v[84:87]
	v_mfma_f32_16x16x32_bf16 v[80:83], v[182:185], v[216:219], v[80:83]
	v_mfma_f32_16x16x32_bf16 v[68:71], v[174:177], v[234:237], v[68:71]
	v_mfma_f32_16x16x32_bf16 v[64:67], v[182:185], v[234:237], v[64:67]
	s_setprio 0
	s_barrier
; #define PG8_STAGE(bufoff, gbase, voff) do { _Pragma("unroll") for (int _i = 0; _i < 2; ++_i) \
;         __builtin_amdgcn_global_load_lds((const unsigned*)((const char*)(gbase) + (voff)[_i]), (PG8_LAS unsigned*)(lds + (bufoff) + ldsw + _i * 8192), 16, 0, 0); } while (0)
; #define PG8_LDA(dst, b, h) do { _Pragma("unroll") for (int m = 0; m < 4; ++m) _Pragma("unroll") for (int k = 0; k < 2; ++k) dst[m][k] = *(const PG8_LAS bf16x8*)(lds + PG8_SA(b, h) + aoff + m * 2048 + k * 1024); } while (0)
; #define PG8_MMA(ai, bj, At, Bt) do { __builtin_amdgcn_s_setprio(1); _Pragma("unroll") for (int m = 0; m < 4; ++m) _Pragma("unroll") for (int n = 0; n < 2; ++n) _Pragma("unroll") for (int k = 0; k < 2; ++k) \
;         acc[ai][bj][m][n] = __builtin_amdgcn_mfma_f32_16x16x32_bf16(Bt[n][k], At[m][k], acc[ai][bj][m][n], 0, 0, 0); __builtin_amdgcn_s_setprio(0); } while (0)
; #define PG8_WAIT_V(n) asm volatile("s_waitcnt vmcnt(" #n ")" ::: "memory")
; #define PG8_WAIT_L(n) asm volatile("s_waitcnt lgkmcnt(" #n ")" ::: "memory")
; #define PG8_BAR __builtin_amdgcn_s_barrier()
; #define PG8_SCHED __builtin_amdgcn_sched_barrier(0)
; template <class Epi, class Sched, bool ALIGN_EPI = false, bool SP2 = false>
; __device__ __forceinline__ void gemm_phase(PG8_LAS unsigned char* lds, const Gemm g, const Sched& S, const Epi& E, const int tid) {
;     ...
;             PG8_LDA(At, 1, 1); PG8_STAGE(PG8_SB(1, 0), b3, voffB); PG8_STAGE(PG8_SB(1, 1), b3 + hstepB, voffB); PG8_STAGE(PG8_SA(1, 0), a3, voffA);
;             PG8_WAIT_V(8); PG8_WAIT_L(0); PG8_BAR; PG8_MMA(1, 0, At, B0); PG8_MMA(1, 1, At, B1); PG8_BAR; PG8_SCHED;
;     ...
;         if constexpr (ALIGN_EPI) { if (wr == 0) PG8_BAR; }
	s_add_i32 s42, s48, s65
	v_lshl_add_u64 v[142:143], v[142:143], 0, s[60:61]
	s_mov_b32 m0, s42
	ds_read_b128 v[186:189], v157 offset:49152
	ds_read_b128 v[200:203], v157 offset:50176
	ds_read_b128 v[204:207], v157 offset:51200
	ds_read_b128 v[208:211], v157 offset:52224
	ds_read_b128 v[212:215], v157 offset:53248
	ds_read_b128 v[216:219], v157 offset:54272
	ds_read_b128 v[220:223], v157 offset:55296
	ds_read_b128 v[234:237], v157 offset:56320
	global_load_lds_dwordx4 v[142:143], off
	v_lshl_add_u64 v[142:143], v[190:191], 0, s[60:61]
	s_add_i32 m0, s42, 0x2000
	s_add_i32 s42, s49, s65
	global_load_lds_dwordx4 v[142:143], off
	v_lshl_add_u64 v[142:143], v[238:239], 0, s[60:61]
	s_mov_b32 m0, s42
	s_nop 0
	global_load_lds_dwordx4 v[142:143], off
	v_lshl_add_u64 v[142:143], v[240:241], 0, s[60:61]
	s_add_i32 m0, s42, 0x2000
	s_nop 0
	global_load_lds_dwordx4 v[142:143], off
	v_lshl_add_u64 v[142:143], v[242:243], 0, s[60:61]
	s_mov_b32 m0, s85
	s_nop 0
	global_load_lds_dwordx4 v[142:143], off
	v_lshl_add_u64 v[142:143], v[244:245], 0, s[60:61]
	s_mov_b32 m0, s86
	s_nop 0
	global_load_lds_dwordx4 v[142:143], off
	s_waitcnt vmcnt(8) lgkmcnt(0)
	s_barrier
	s_setprio 1
	v_mfma_f32_16x16x32_bf16 v[60:63], v[138:141], v[186:189], v[60:63]
	v_mfma_f32_16x16x32_bf16 v[56:59], v[162:165], v[186:189], v[56:59]
	v_mfma_f32_16x16x32_bf16 v[44:47], v[138:141], v[204:207], v[44:47]
	v_mfma_f32_16x16x32_bf16 v[40:43], v[162:165], v[204:207], v[40:43]
	v_mfma_f32_16x16x32_bf16 v[28:31], v[138:141], v[212:215], v[28:31]
	v_mfma_f32_16x16x32_bf16 v[24:27], v[162:165], v[212:215], v[24:27]
	v_mfma_f32_16x16x32_bf16 v[12:15], v[138:141], v[220:223], v[12:15]
	v_mfma_f32_16x16x32_bf16 v[8:11], v[162:165], v[220:223], v[8:11]
	v_mfma_f32_16x16x32_bf16 v[60:63], v[158:161], v[200:203], v[60:63]
	v_mfma_f32_16x16x32_bf16 v[56:59], v[166:169], v[200:203], v[56:59]
	v_mfma_f32_16x16x32_bf16 v[44:47], v[158:161], v[208:211], v[44:47]
	v_mfma_f32_16x16x32_bf16 v[40:43], v[166:169], v[208:211], v[40:43]
	v_mfma_f32_16x16x32_bf16 v[28:31], v[158:161], v[216:219], v[28:31]
	v_mfma_f32_16x16x32_bf16 v[24:27], v[166:169], v[216:219], v[24:27]
	v_mfma_f32_16x16x32_bf16 v[12:15], v[158:161], v[234:237], v[12:15]
	v_mfma_f32_16x16x32_bf16 v[8:11], v[166:169], v[234:237], v[8:11]
	s_setprio 0
	s_setprio 1
	v_mfma_f32_16x16x32_bf16 v[52:55], v[170:173], v[186:189], v[52:55]
	v_mfma_f32_16x16x32_bf16 v[48:51], v[178:181], v[186:189], v[48:51]
	v_mfma_f32_16x16x32_bf16 v[36:39], v[170:173], v[204:207], v[36:39]
	v_mfma_f32_16x16x32_bf16 v[32:35], v[178:181], v[204:207], v[32:35]
	v_mfma_f32_16x16x32_bf16 v[20:23], v[170:173], v[212:215], v[20:23]
	v_mfma_f32_16x16x32_bf16 v[16:19], v[178:181], v[212:215], v[16:19]
	v_mfma_f32_16x16x32_bf16 v[4:7], v[170:173], v[220:223], v[4:7]
	v_mfma_f32_16x16x32_bf16 v[0:3], v[178:181], v[220:223], v[0:3]
	v_mfma_f32_16x16x32_bf16 v[52:55], v[174:177], v[200:203], v[52:55]
	v_mfma_f32_16x16x32_bf16 v[48:51], v[182:185], v[200:203], v[48:51]
	v_mfma_f32_16x16x32_bf16 v[36:39], v[174:177], v[208:211], v[36:39]
	v_mfma_f32_16x16x32_bf16 v[32:35], v[182:185], v[208:211], v[32:35]
	v_mfma_f32_16x16x32_bf16 v[20:23], v[174:177], v[216:219], v[20:23]
	v_mfma_f32_16x16x32_bf16 v[16:19], v[182:185], v[216:219], v[16:19]
	v_mfma_f32_16x16x32_bf16 v[4:7], v[174:177], v[234:237], v[4:7]
	v_mfma_f32_16x16x32_bf16 v[0:3], v[182:185], v[234:237], v[0:3]
	s_setprio 0
	s_barrier
	s_add_u32 s24, s24, 0x100
	s_addc_u32 s25, s25, 0
	s_cmp_ge_u32 vcc_lo, s84
	s_mov_b64 s[48:49], s[50:51]
	s_mov_b32 s52, vcc_lo
	s_cbranch_scc0 .LBB0_248
	s_and_b64 vcc, exec, s[18:19]
	s_cbranch_vccz .LBB0_251
	s_barrier

; #define PG8_STAGE(bufoff, gbase, voff) do { _Pragma("unroll") for (int _i = 0; _i < 2; ++_i) \
;         __builtin_amdgcn_global_load_lds((const unsigned*)((const char*)(gbase) + (voff)[_i]), (PG8_LAS unsigned*)(lds + (bufoff) + ldsw + _i * 8192), 16, 0, 0); } while (0)
; #define PG8_LDA(dst, b, h) do { _Pragma("unroll") for (int m = 0; m < 4; ++m) _Pragma("unroll") for (int k = 0; k < 2; ++k) dst[m][k] = *(const PG8_LAS bf16x8*)(lds + PG8_SA(b, h) + aoff + m * 2048 + k * 1024); } while (0)
; #define PG8_LDB(dst, b, h) do { _Pragma("unroll") for (int n = 0; n < 2; ++n) _Pragma("unroll") for (int k = 0; k < 2; ++k) dst[n][k] = *(const PG8_LAS bf16x8*)(lds + PG8_SB(b, h) + boff + n * 2048 + k * 1024); } while (0)
; #define PG8_MMA(ai, bj, At, Bt) do { __builtin_amdgcn_s_setprio(1); _Pragma("unroll") for (int m = 0; m < 4; ++m) _Pragma("unroll") for (int n = 0; n < 2; ++n) _Pragma("unroll") for (int k = 0; k < 2; ++k) \
;         acc[ai][bj][m][n] = __builtin_amdgcn_mfma_f32_16x16x32_bf16(Bt[n][k], At[m][k], acc[ai][bj][m][n], 0, 0, 0); __builtin_amdgcn_s_setprio(0); } while (0)
; #define PG8_WAIT_V(n) asm volatile("s_waitcnt vmcnt(" #n ")" ::: "memory")
; #define PG8_WAIT_L(n) asm volatile("s_waitcnt lgkmcnt(" #n ")" ::: "memory")
; template <class Epi, class Sched, bool ALIGN_EPI = false, bool SP2 = false>
; __device__ __forceinline__ void gemm_phase(PG8_LAS unsigned char* lds, const Gemm g, const Sched& S, const Epi& E, const int tid) {
;     ...
;             const bool last = (t == nt - 2);
;             const char* a1 = cA + (size_t)(t + 1) * kstep;
;             const char* a2 = last ? nA : cA + (size_t)(t + 2) * kstep; const char* b2 = last ? nB : cB + (size_t)(t + 2) * kstep;
;             const char* a3 = a2 + kstep; const char* b3 = b2 + kstep;
;             if (last && has_next) S.a_ready(nxt);
;             if constexpr (SP2) {
;             PG8_LDB(B0, 0, 0); PG8_LDB(B1, 0, 1); PG8_SCHED; PG8_LDA(At, 0, 0); PG8_STAGE(PG8_SA(1, 1), a1 + hstepA, voffA);
;             PG8_WAIT_V(8); PG8_WAIT_L(0); PG8_BAR; PG8_MMA(0, 0, At, B0); PG8_MMA(0, 1, At, B1); PG8_BAR; PG8_SCHED;
;             PG8_LDA(At, 0, 1); PG8_STAGE(PG8_SB(0, 0), b2, voffB); PG8_STAGE(PG8_SB(0, 1), b2 + hstepB, voffB); PG8_STAGE(PG8_SA(0, 0), a2, voffA);
;             PG8_WAIT_V(8); PG8_WAIT_L(0); PG8_BAR; PG8_MMA(1, 0, At, B0); PG8_MMA(1, 1, At, B1); PG8_BAR; PG8_SCHED;
.LBB0_313:
	s_add_u32 s24, s50, 0xfffc0080
	s_addc_u32 s25, s51, -1
	s_add_i32 s68, 0, 0x10000
	s_cmp_eq_u32 s65, 12
	s_cselect_b32 s55, s40, s25
	s_cselect_b32 s54, s43, s24
	s_cselect_b32 s53, s39, s63
	s_cselect_b32 s52, s58, s59
	s_add_i32 s69, 0, 0x14000
	v_add_u32_e32 v154, s68, v139
	v_add_u32_e32 v170, s69, v139
	ds_read_b128 v[142:145], v154
	ds_read_b128 v[146:149], v154 offset:1024
	ds_read_b128 v[150:153], v154 offset:2048
	ds_read_b128 v[154:157], v154 offset:3072
	ds_read_b128 v[158:161], v170
	ds_read_b128 v[162:165], v170 offset:1024
	ds_read_b128 v[166:169], v170 offset:2048
	ds_read_b128 v[170:173], v170 offset:3072
	v_lshl_add_u64 v[190:191], s[50:51], 0, v[136:137]
	s_add_i32 m0, s21, 0xc000
	ds_read_b128 v[174:177], v141
	ds_read_b128 v[178:181], v141 offset:1024
	ds_read_b128 v[182:185], v141 offset:2048
	ds_read_b128 v[186:189], v141 offset:3072
	ds_read_b128 v[200:203], v141 offset:4096
	ds_read_b128 v[204:207], v141 offset:5120
	ds_read_b128 v[208:211], v141 offset:6144
	ds_read_b128 v[212:215], v141 offset:7168
	global_load_lds_dwordx4 v[190:191], off
	v_lshl_add_u64 v[190:191], s[50:51], 0, v[134:135]
	s_add_i32 m0, s21, 0xe000
	s_nop 0
	global_load_lds_dwordx4 v[190:191], off
	s_waitcnt vmcnt(8) lgkmcnt(0)
	s_barrier
	s_setprio 1
	v_mfma_f32_16x16x32_bf16 v[124:127], v[142:145], v[174:177], v[124:127]
	v_mfma_f32_16x16x32_bf16 v[120:123], v[150:153], v[174:177], v[120:123]
	v_mfma_f32_16x16x32_bf16 v[116:119], v[142:145], v[182:185], v[116:119]
	v_mfma_f32_16x16x32_bf16 v[112:115], v[150:153], v[182:185], v[112:115]
	v_mfma_f32_16x16x32_bf16 v[100:103], v[142:145], v[200:203], v[100:103]
	v_mfma_f32_16x16x32_bf16 v[96:99], v[150:153], v[200:203], v[96:99]
	v_mfma_f32_16x16x32_bf16 v[84:87], v[142:145], v[208:211], v[84:87]
	v_mfma_f32_16x16x32_bf16 v[80:83], v[150:153], v[208:211], v[80:83]
	v_mfma_f32_16x16x32_bf16 v[124:127], v[146:149], v[178:181], v[124:127]
	v_mfma_f32_16x16x32_bf16 v[120:123], v[154:157], v[178:181], v[120:123]
	v_mfma_f32_16x16x32_bf16 v[116:119], v[146:149], v[186:189], v[116:119]
	v_mfma_f32_16x16x32_bf16 v[112:115], v[154:157], v[186:189], v[112:115]
	v_mfma_f32_16x16x32_bf16 v[100:103], v[146:149], v[204:207], v[100:103]
	v_mfma_f32_16x16x32_bf16 v[96:99], v[154:157], v[204:207], v[96:99]
	v_mfma_f32_16x16x32_bf16 v[84:87], v[146:149], v[212:215], v[84:87]
	v_mfma_f32_16x16x32_bf16 v[80:83], v[154:157], v[212:215], v[80:83]
	s_setprio 0
	s_setprio 1
	v_mfma_f32_16x16x32_bf16 v[108:111], v[158:161], v[174:177], v[108:111]
	v_mfma_f32_16x16x32_bf16 v[104:107], v[166:169], v[174:177], v[104:107]
	v_mfma_f32_16x16x32_bf16 v[92:95], v[158:161], v[182:185], v[92:95]
	v_mfma_f32_16x16x32_bf16 v[88:91], v[166:169], v[182:185], v[88:91]
	v_mfma_f32_16x16x32_bf16 v[76:79], v[158:161], v[200:203], v[76:79]
	v_mfma_f32_16x16x32_bf16 v[72:75], v[166:169], v[200:203], v[72:75]
	v_mfma_f32_16x16x32_bf16 v[68:71], v[158:161], v[208:211], v[68:71]
	v_mfma_f32_16x16x32_bf16 v[64:67], v[166:169], v[208:211], v[64:67]
	v_mfma_f32_16x16x32_bf16 v[108:111], v[162:165], v[178:181], v[108:111]
	v_mfma_f32_16x16x32_bf16 v[104:107], v[170:173], v[178:181], v[104:107]
	v_mfma_f32_16x16x32_bf16 v[92:95], v[162:165], v[186:189], v[92:95]
	v_mfma_f32_16x16x32_bf16 v[88:91], v[170:173], v[186:189], v[88:91]
	v_mfma_f32_16x16x32_bf16 v[76:79], v[162:165], v[204:207], v[76:79]
	v_mfma_f32_16x16x32_bf16 v[72:75], v[170:173], v[204:207], v[72:75]
	v_mfma_f32_16x16x32_bf16 v[68:71], v[162:165], v[212:215], v[68:71]
	v_mfma_f32_16x16x32_bf16 v[64:67], v[170:173], v[212:215], v[64:67]
	s_setprio 0
	s_barrier
	s_add_i32 s24, s68, s20
	v_lshl_add_u64 v[190:191], s[52:53], 0, v[192:193]
	s_mov_b32 m0, s24
	ds_read_b128 v[174:177], v141 offset:16384
	ds_read_b128 v[178:181], v141 offset:17408
	ds_read_b128 v[182:185], v141 offset:18432
	ds_read_b128 v[186:189], v141 offset:19456
	ds_read_b128 v[200:203], v141 offset:20480
	ds_read_b128 v[204:207], v141 offset:21504
	ds_read_b128 v[208:211], v141 offset:22528
	ds_read_b128 v[212:215], v141 offset:23552
	global_load_lds_dwordx4 v[190:191], off
	s_add_i32 m0, s24, 0x2000
	s_add_u32 s24, s52, 0x40000
	v_lshl_add_u64 v[216:217], s[52:53], 0, v[128:129]
	s_addc_u32 s25, s53, 0
	s_add_i32 s68, s69, s20
	global_load_lds_dwordx4 v[216:217], off
	v_lshl_add_u64 v[218:219], s[24:25], 0, v[192:193]
	s_mov_b32 m0, s68
	v_lshl_add_u64 v[220:221], s[54:55], 0, v[130:131]
	global_load_lds_dwordx4 v[218:219], off
	v_lshl_add_u64 v[218:219], s[24:25], 0, v[128:129]
	s_add_i32 m0, s68, 0x2000
	s_nop 0
	global_load_lds_dwordx4 v[218:219], off
	v_lshl_add_u64 v[218:219], s[54:55], 0, v[132:133]
	s_mov_b32 m0, s21
	s_nop 0
	global_load_lds_dwordx4 v[218:219], off
	s_mov_b32 m0, s26
	s_nop 0
	global_load_lds_dwordx4 v[220:221], off
	s_waitcnt vmcnt(8) lgkmcnt(0)
	s_barrier
; #define PG8_STAGE(bufoff, gbase, voff) do { _Pragma("unroll") for (int _i = 0; _i < 2; ++_i) \
;         __builtin_amdgcn_global_load_lds((const unsigned*)((const char*)(gbase) + (voff)[_i]), (PG8_LAS unsigned*)(lds + (bufoff) + ldsw + _i * 8192), 16, 0, 0); } while (0)
; #define PG8_LDA(dst, b, h) do { _Pragma("unroll") for (int m = 0; m < 4; ++m) _Pragma("unroll") for (int k = 0; k < 2; ++k) dst[m][k] = *(const PG8_LAS bf16x8*)(lds + PG8_SA(b, h) + aoff + m * 2048 + k * 1024); } while (0)
; #define PG8_LDB(dst, b, h) do { _Pragma("unroll") for (int n = 0; n < 2; ++n) _Pragma("unroll") for (int k = 0; k < 2; ++k) dst[n][k] = *(const PG8_LAS bf16x8*)(lds + PG8_SB(b, h) + boff + n * 2048 + k * 1024); } while (0)
; #define PG8_MMA(ai, bj, At, Bt) do { __builtin_amdgcn_s_setprio(1); _Pragma("unroll") for (int m = 0; m < 4; ++m) _Pragma("unroll") for (int n = 0; n < 2; ++n) _Pragma("unroll") for (int k = 0; k < 2; ++k) \
;         acc[ai][bj][m][n] = __builtin_amdgcn_mfma_f32_16x16x32_bf16(Bt[n][k], At[m][k], acc[ai][bj][m][n], 0, 0, 0); __builtin_amdgcn_s_setprio(0); } while (0)
; #define PG8_WAIT_V(n) asm volatile("s_waitcnt vmcnt(" #n ")" ::: "memory")
; #define PG8_WAIT_L(n) asm volatile("s_waitcnt lgkmcnt(" #n ")" ::: "memory")
; #define PG8_BAR __builtin_amdgcn_s_barrier()
; #define PG8_SCHED __builtin_amdgcn_sched_barrier(0)
; template <class Epi, class Sched, bool ALIGN_EPI = false, bool SP2 = false>
; __device__ __forceinline__ void gemm_phase(PG8_LAS unsigned char* lds, const Gemm g, const Sched& S, const Epi& E, const int tid) {
;     ...
;             PG8_WAIT_V(8); PG8_WAIT_L(0); PG8_BAR; PG8_MMA(1, 0, At, B0); PG8_MMA(1, 1, At, B1); PG8_BAR; PG8_SCHED;
;             PG8_LDB(B0, 1, 0); PG8_LDB(B1, 1, 1); PG8_SCHED; PG8_LDA(At, 1, 0); PG8_STAGE(PG8_SA(0, 1), a2 + hstepA, voffA);
;             PG8_WAIT_V(8); PG8_WAIT_L(0); PG8_BAR; PG8_MMA(0, 0, At, B0); PG8_MMA(0, 1, At, B1); PG8_BAR; PG8_SCHED;
	s_setprio 1
	v_mfma_f32_16x16x32_bf16 v[60:63], v[142:145], v[174:177], v[60:63]
	v_mfma_f32_16x16x32_bf16 v[56:59], v[150:153], v[174:177], v[56:59]
	v_mfma_f32_16x16x32_bf16 v[52:55], v[142:145], v[182:185], v[52:55]
	v_mfma_f32_16x16x32_bf16 v[48:51], v[150:153], v[182:185], v[48:51]
	v_mfma_f32_16x16x32_bf16 v[36:39], v[142:145], v[200:203], v[36:39]
	v_mfma_f32_16x16x32_bf16 v[32:35], v[150:153], v[200:203], v[32:35]
	v_mfma_f32_16x16x32_bf16 v[20:23], v[142:145], v[208:211], v[20:23]
	v_mfma_f32_16x16x32_bf16 v[16:19], v[150:153], v[208:211], v[16:19]
	v_mfma_f32_16x16x32_bf16 v[60:63], v[146:149], v[178:181], v[60:63]
	v_mfma_f32_16x16x32_bf16 v[56:59], v[154:157], v[178:181], v[56:59]
	v_mfma_f32_16x16x32_bf16 v[52:55], v[146:149], v[186:189], v[52:55]
	v_mfma_f32_16x16x32_bf16 v[48:51], v[154:157], v[186:189], v[48:51]
	v_mfma_f32_16x16x32_bf16 v[36:39], v[146:149], v[204:207], v[36:39]
	v_mfma_f32_16x16x32_bf16 v[32:35], v[154:157], v[204:207], v[32:35]
	v_mfma_f32_16x16x32_bf16 v[20:23], v[146:149], v[212:215], v[20:23]
	v_mfma_f32_16x16x32_bf16 v[16:19], v[154:157], v[212:215], v[16:19]
	s_setprio 0
	s_setprio 1
	v_mfma_f32_16x16x32_bf16 v[44:47], v[158:161], v[174:177], v[44:47]
	v_mfma_f32_16x16x32_bf16 v[40:43], v[166:169], v[174:177], v[40:43]
	v_mfma_f32_16x16x32_bf16 v[28:31], v[158:161], v[182:185], v[28:31]
	v_mfma_f32_16x16x32_bf16 v[24:27], v[166:169], v[182:185], v[24:27]
	v_mfma_f32_16x16x32_bf16 v[12:15], v[158:161], v[200:203], v[12:15]
	v_mfma_f32_16x16x32_bf16 v[8:11], v[166:169], v[200:203], v[8:11]
	v_mfma_f32_16x16x32_bf16 v[4:7], v[158:161], v[208:211], v[4:7]
	v_mfma_f32_16x16x32_bf16 v[0:3], v[166:169], v[208:211], v[0:3]
	v_mfma_f32_16x16x32_bf16 v[44:47], v[162:165], v[178:181], v[44:47]
	v_mfma_f32_16x16x32_bf16 v[40:43], v[170:173], v[178:181], v[40:43]
	v_mfma_f32_16x16x32_bf16 v[28:31], v[162:165], v[186:189], v[28:31]
	v_mfma_f32_16x16x32_bf16 v[24:27], v[170:173], v[186:189], v[24:27]
	v_mfma_f32_16x16x32_bf16 v[12:15], v[162:165], v[204:207], v[12:15]
	v_mfma_f32_16x16x32_bf16 v[8:11], v[170:173], v[204:207], v[8:11]
	v_mfma_f32_16x16x32_bf16 v[4:7], v[162:165], v[212:215], v[4:7]
	v_mfma_f32_16x16x32_bf16 v[0:3], v[170:173], v[212:215], v[0:3]
	s_setprio 0
	s_barrier
	s_add_i32 s68, 0, 0x18000
	s_add_i32 s69, 0, 0x1c000
	v_add_u32_e32 v154, s68, v139
	v_add_u32_e32 v170, s69, v139
	ds_read_b128 v[142:145], v154
	ds_read_b128 v[146:149], v154 offset:1024
	ds_read_b128 v[150:153], v154 offset:2048
	ds_read_b128 v[154:157], v154 offset:3072
	ds_read_b128 v[158:161], v170
	ds_read_b128 v[162:165], v170 offset:1024
	ds_read_b128 v[166:169], v170 offset:2048
	ds_read_b128 v[170:173], v170 offset:3072
	s_add_u32 s24, s54, 0x40000
	s_addc_u32 s25, s55, 0
	s_mov_b32 m0, s27
	v_lshl_add_u64 v[222:223], s[24:25], 0, v[132:133]
	ds_read_b128 v[174:177], v141 offset:32768
	ds_read_b128 v[178:181], v141 offset:33792
	ds_read_b128 v[182:185], v141 offset:34816
	ds_read_b128 v[186:189], v141 offset:35840
	ds_read_b128 v[200:203], v141 offset:36864
	ds_read_b128 v[204:207], v141 offset:37888
	ds_read_b128 v[208:211], v141 offset:38912
	ds_read_b128 v[212:215], v141 offset:39936
	global_load_lds_dwordx4 v[222:223], off
	v_lshl_add_u64 v[222:223], s[24:25], 0, v[130:131]
	s_mov_b32 m0, s28
	s_nop 0
	global_load_lds_dwordx4 v[222:223], off
	s_waitcnt vmcnt(8) lgkmcnt(0)
	s_barrier
	s_setprio 1
	v_mfma_f32_16x16x32_bf16 v[124:127], v[142:145], v[174:177], v[124:127]
	v_mfma_f32_16x16x32_bf16 v[120:123], v[150:153], v[174:177], v[120:123]
	v_mfma_f32_16x16x32_bf16 v[116:119], v[142:145], v[182:185], v[116:119]
	v_mfma_f32_16x16x32_bf16 v[112:115], v[150:153], v[182:185], v[112:115]
	v_mfma_f32_16x16x32_bf16 v[100:103], v[142:145], v[200:203], v[100:103]
	v_mfma_f32_16x16x32_bf16 v[96:99], v[150:153], v[200:203], v[96:99]
	v_mfma_f32_16x16x32_bf16 v[84:87], v[142:145], v[208:211], v[84:87]
	v_mfma_f32_16x16x32_bf16 v[80:83], v[150:153], v[208:211], v[80:83]
	v_mfma_f32_16x16x32_bf16 v[124:127], v[146:149], v[178:181], v[124:127]
	v_mfma_f32_16x16x32_bf16 v[120:123], v[154:157], v[178:181], v[120:123]
	v_mfma_f32_16x16x32_bf16 v[116:119], v[146:149], v[186:189], v[116:119]
	v_mfma_f32_16x16x32_bf16 v[112:115], v[154:157], v[186:189], v[112:115]
	v_mfma_f32_16x16x32_bf16 v[100:103], v[146:149], v[204:207], v[100:103]
	v_mfma_f32_16x16x32_bf16 v[96:99], v[154:157], v[204:207], v[96:99]
	v_mfma_f32_16x16x32_bf16 v[84:87], v[146:149], v[212:215], v[84:87]
	v_mfma_f32_16x16x32_bf16 v[80:83], v[154:157], v[212:215], v[80:83]
	s_setprio 0
	s_setprio 1
	v_mfma_f32_16x16x32_bf16 v[108:111], v[158:161], v[174:177], v[108:111]
	v_mfma_f32_16x16x32_bf16 v[104:107], v[166:169], v[174:177], v[104:107]
	v_mfma_f32_16x16x32_bf16 v[92:95], v[158:161], v[182:185], v[92:95]
	v_mfma_f32_16x16x32_bf16 v[88:91], v[166:169], v[182:185], v[88:91]
	v_mfma_f32_16x16x32_bf16 v[76:79], v[158:161], v[200:203], v[76:79]
	v_mfma_f32_16x16x32_bf16 v[72:75], v[166:169], v[200:203], v[72:75]
	v_mfma_f32_16x16x32_bf16 v[68:71], v[158:161], v[208:211], v[68:71]
	v_mfma_f32_16x16x32_bf16 v[64:67], v[166:169], v[208:211], v[64:67]
	v_mfma_f32_16x16x32_bf16 v[108:111], v[162:165], v[178:181], v[108:111]
	v_mfma_f32_16x16x32_bf16 v[104:107], v[170:173], v[178:181], v[104:107]
	v_mfma_f32_16x16x32_bf16 v[92:95], v[162:165], v[186:189], v[92:95]
	v_mfma_f32_16x16x32_bf16 v[88:91], v[170:173], v[186:189], v[88:91]
	v_mfma_f32_16x16x32_bf16 v[76:79], v[162:165], v[204:207], v[76:79]
	v_mfma_f32_16x16x32_bf16 v[72:75], v[170:173], v[204:207], v[72:75]
	v_mfma_f32_16x16x32_bf16 v[68:71], v[162:165], v[212:215], v[68:71]
	v_mfma_f32_16x16x32_bf16 v[64:67], v[170:173], v[212:215], v[64:67]
	s_setprio 0
	s_barrier
; #define PG8_STAGE(bufoff, gbase, voff) do { _Pragma("unroll") for (int _i = 0; _i < 2; ++_i) \
;         __builtin_amdgcn_global_load_lds((const unsigned*)((const char*)(gbase) + (voff)[_i]), (PG8_LAS unsigned*)(lds + (bufoff) + ldsw + _i * 8192), 16, 0, 0); } while (0)
; #define PG8_LDA(dst, b, h) do { _Pragma("unroll") for (int m = 0; m < 4; ++m) _Pragma("unroll") for (int k = 0; k < 2; ++k) dst[m][k] = *(const PG8_LAS bf16x8*)(lds + PG8_SA(b, h) + aoff + m * 2048 + k * 1024); } while (0)
; #define PG8_MMA(ai, bj, At, Bt) do { __builtin_amdgcn_s_setprio(1); _Pragma("unroll") for (int m = 0; m < 4; ++m) _Pragma("unroll") for (int n = 0; n < 2; ++n) _Pragma("unroll") for (int k = 0; k < 2; ++k) \
;         acc[ai][bj][m][n] = __builtin_amdgcn_mfma_f32_16x16x32_bf16(Bt[n][k], At[m][k], acc[ai][bj][m][n], 0, 0, 0); __builtin_amdgcn_s_setprio(0); } while (0)
; #define PG8_WAIT_V(n) asm volatile("s_waitcnt vmcnt(" #n ")" ::: "memory")
; #define PG8_WAIT_L(n) asm volatile("s_waitcnt lgkmcnt(" #n ")" ::: "memory")
; #define PG8_BAR __builtin_amdgcn_s_barrier()
; #define PG8_SCHED __builtin_amdgcn_sched_barrier(0)
; template <class Epi, class Sched, bool ALIGN_EPI = false, bool SP2 = false>
; __device__ __forceinline__ void gemm_phase(PG8_LAS unsigned char* lds, const Gemm g, const Sched& S, const Epi& E, const int tid) {
;     ...
;             PG8_LDA(At, 1, 1); PG8_STAGE(PG8_SB(1, 0), b3, voffB); PG8_STAGE(PG8_SB(1, 1), b3 + hstepB, voffB); PG8_STAGE(PG8_SA(1, 0), a3, voffA);
;             PG8_WAIT_V(8); PG8_WAIT_L(0); PG8_BAR; PG8_MMA(1, 0, At, B0); PG8_MMA(1, 1, At, B1); PG8_BAR; PG8_SCHED;
;     ...
;         if constexpr (ALIGN_EPI) { if (wr == 0) PG8_BAR; }
	s_add_i32 s24, s68, s20
	v_lshl_add_u64 v[190:191], v[190:191], 0, s[60:61]
	s_mov_b32 m0, s24
	ds_read_b128 v[174:177], v141 offset:49152
	ds_read_b128 v[178:181], v141 offset:50176
	ds_read_b128 v[182:185], v141 offset:51200
	ds_read_b128 v[186:189], v141 offset:52224
	ds_read_b128 v[200:203], v141 offset:53248
	ds_read_b128 v[204:207], v141 offset:54272
	ds_read_b128 v[208:211], v141 offset:55296
	ds_read_b128 v[212:215], v141 offset:56320
	global_load_lds_dwordx4 v[190:191], off
	s_add_i32 m0, s24, 0x2000
	s_add_u32 s24, s52, 0x40080
	v_lshl_add_u64 v[190:191], v[216:217], 0, s[60:61]
	s_addc_u32 s25, s53, 0
	s_add_i32 s52, s69, s20
	global_load_lds_dwordx4 v[190:191], off
	v_lshl_add_u64 v[190:191], s[24:25], 0, v[192:193]
	s_mov_b32 m0, s52
	s_nop 0
	global_load_lds_dwordx4 v[190:191], off
	v_lshl_add_u64 v[190:191], s[24:25], 0, v[128:129]
	s_add_i32 m0, s52, 0x2000
	s_nop 0
	global_load_lds_dwordx4 v[190:191], off
	v_lshl_add_u64 v[190:191], v[218:219], 0, s[60:61]
	s_mov_b32 m0, s29
	s_nop 0
	global_load_lds_dwordx4 v[190:191], off
	v_lshl_add_u64 v[190:191], v[220:221], 0, s[60:61]
	s_mov_b32 m0, s36
	s_nop 0
	global_load_lds_dwordx4 v[190:191], off
	s_waitcnt vmcnt(8) lgkmcnt(0)
	s_barrier
	s_setprio 1
	v_mfma_f32_16x16x32_bf16 v[60:63], v[142:145], v[174:177], v[60:63]
	v_mfma_f32_16x16x32_bf16 v[56:59], v[150:153], v[174:177], v[56:59]
	v_mfma_f32_16x16x32_bf16 v[52:55], v[142:145], v[182:185], v[52:55]
	v_mfma_f32_16x16x32_bf16 v[48:51], v[150:153], v[182:185], v[48:51]
	v_mfma_f32_16x16x32_bf16 v[36:39], v[142:145], v[200:203], v[36:39]
	v_mfma_f32_16x16x32_bf16 v[32:35], v[150:153], v[200:203], v[32:35]
	v_mfma_f32_16x16x32_bf16 v[20:23], v[142:145], v[208:211], v[20:23]
	v_mfma_f32_16x16x32_bf16 v[16:19], v[150:153], v[208:211], v[16:19]
	v_mfma_f32_16x16x32_bf16 v[60:63], v[146:149], v[178:181], v[60:63]
	v_mfma_f32_16x16x32_bf16 v[56:59], v[154:157], v[178:181], v[56:59]
	v_mfma_f32_16x16x32_bf16 v[52:55], v[146:149], v[186:189], v[52:55]
	v_mfma_f32_16x16x32_bf16 v[48:51], v[154:157], v[186:189], v[48:51]
	v_mfma_f32_16x16x32_bf16 v[36:39], v[146:149], v[204:207], v[36:39]
	v_mfma_f32_16x16x32_bf16 v[32:35], v[154:157], v[204:207], v[32:35]
	v_mfma_f32_16x16x32_bf16 v[20:23], v[146:149], v[212:215], v[20:23]
	v_mfma_f32_16x16x32_bf16 v[16:19], v[154:157], v[212:215], v[16:19]
	s_setprio 0
	s_setprio 1
	v_mfma_f32_16x16x32_bf16 v[44:47], v[158:161], v[174:177], v[44:47]
	v_mfma_f32_16x16x32_bf16 v[40:43], v[166:169], v[174:177], v[40:43]
	v_mfma_f32_16x16x32_bf16 v[28:31], v[158:161], v[182:185], v[28:31]
	v_mfma_f32_16x16x32_bf16 v[24:27], v[166:169], v[182:185], v[24:27]
	v_mfma_f32_16x16x32_bf16 v[12:15], v[158:161], v[200:203], v[12:15]
	v_mfma_f32_16x16x32_bf16 v[8:11], v[166:169], v[200:203], v[8:11]
	v_mfma_f32_16x16x32_bf16 v[4:7], v[158:161], v[208:211], v[4:7]
	v_mfma_f32_16x16x32_bf16 v[0:3], v[166:169], v[208:211], v[0:3]
	v_mfma_f32_16x16x32_bf16 v[44:47], v[162:165], v[178:181], v[44:47]
	v_mfma_f32_16x16x32_bf16 v[40:43], v[170:173], v[178:181], v[40:43]
	v_mfma_f32_16x16x32_bf16 v[28:31], v[162:165], v[186:189], v[28:31]
	v_mfma_f32_16x16x32_bf16 v[24:27], v[170:173], v[186:189], v[24:27]
	v_mfma_f32_16x16x32_bf16 v[12:15], v[162:165], v[204:207], v[12:15]
	v_mfma_f32_16x16x32_bf16 v[8:11], v[170:173], v[204:207], v[8:11]
	v_mfma_f32_16x16x32_bf16 v[4:7], v[162:165], v[212:215], v[4:7]
	v_mfma_f32_16x16x32_bf16 v[0:3], v[170:173], v[212:215], v[0:3]
	s_setprio 0
	s_barrier
	s_add_i32 s65, s65, 2
	s_add_u32 s59, s59, 0x100
	s_addc_u32 s63, s63, 0
	s_add_u32 s50, s50, 0x100
	s_addc_u32 s51, s51, 0
	s_cmp_gt_u32 s65, 13
	s_cbranch_scc0 .LBB0_313
	s_and_b64 vcc, exec, s[14:15]
	s_cbranch_vccz .LBB0_316
	s_barrier

; #define PG8_STAGE(bufoff, gbase, voff) do { _Pragma("unroll") for (int _i = 0; _i < 2; ++_i) \
;         __builtin_amdgcn_global_load_lds((const unsigned*)((const char*)(gbase) + (voff)[_i]), (PG8_LAS unsigned*)(lds + (bufoff) + ldsw + _i * 8192), 16, 0, 0); } while (0)
; #define PG8_LDA(dst, b, h) do { _Pragma("unroll") for (int m = 0; m < 4; ++m) _Pragma("unroll") for (int k = 0; k < 2; ++k) dst[m][k] = *(const PG8_LAS bf16x8*)(lds + PG8_SA(b, h) + aoff + m * 2048 + k * 1024); } while (0)
; #define PG8_LDB(dst, b, h) do { _Pragma("unroll") for (int n = 0; n < 2; ++n) _Pragma("unroll") for (int k = 0; k < 2; ++k) dst[n][k] = *(const PG8_LAS bf16x8*)(lds + PG8_SB(b, h) + boff + n * 2048 + k * 1024); } while (0)
; #define PG8_MMA(ai, bj, At, Bt) do { __builtin_amdgcn_s_setprio(1); _Pragma("unroll") for (int m = 0; m < 4; ++m) _Pragma("unroll") for (int n = 0; n < 2; ++n) _Pragma("unroll") for (int k = 0; k < 2; ++k) \
;         acc[ai][bj][m][n] = __builtin_amdgcn_mfma_f32_16x16x32_bf16(Bt[n][k], At[m][k], acc[ai][bj][m][n], 0, 0, 0); __builtin_amdgcn_s_setprio(0); } while (0)
; #define PG8_WAIT_V(n) asm volatile("s_waitcnt vmcnt(" #n ")" ::: "memory")
; #define PG8_WAIT_L(n) asm volatile("s_waitcnt lgkmcnt(" #n ")" ::: "memory")
; template <class Epi, class Sched, bool ALIGN_EPI = false, bool SP2 = false>
; __device__ __forceinline__ void gemm_phase(PG8_LAS unsigned char* lds, const Gemm g, const Sched& S, const Epi& E, const int tid) {
;     ...
;             const bool last = (t == nt - 2);
;             const char* a1 = cA + (size_t)(t + 1) * kstep;
;             const char* a2 = last ? nA : cA + (size_t)(t + 2) * kstep; const char* b2 = last ? nB : cB + (size_t)(t + 2) * kstep;
;             const char* a3 = a2 + kstep; const char* b3 = b2 + kstep;
;             if (last && has_next) S.a_ready(nxt);
;             if constexpr (SP2) {
;             PG8_LDB(B0, 0, 0); PG8_LDB(B1, 0, 1); PG8_SCHED; PG8_LDA(At, 0, 0); PG8_STAGE(PG8_SA(1, 1), a1 + hstepA, voffA);
;             PG8_WAIT_V(8); PG8_WAIT_L(0); PG8_BAR; PG8_MMA(0, 0, At, B0); PG8_MMA(0, 1, At, B1); PG8_BAR; PG8_SCHED;
;             PG8_LDA(At, 0, 1); PG8_STAGE(PG8_SB(0, 0), b2, voffB); PG8_STAGE(PG8_SB(0, 1), b2 + hstepB, voffB); PG8_STAGE(PG8_SA(0, 0), a2, voffA);
;             PG8_WAIT_V(8); PG8_WAIT_L(0); PG8_BAR; PG8_MMA(1, 0, At, B0); PG8_MMA(1, 1, At, B1); PG8_BAR; PG8_SCHED;
.LBB0_347:
	s_add_u32 s48, s10, 0x100
	s_addc_u32 s49, s11, 0
	s_add_i32 s25, 0, 0x10000
	s_cmp_eq_u32 s24, 40
	s_cselect_b32 s53, s45, s49
	s_cselect_b32 s52, s44, s48
	s_cselect_b32 s51, s47, s21
	s_cselect_b32 s50, s46, s20
	s_add_i32 s26, 0, 0x14000
	v_add_u32_e32 v72, s25, v197
	v_add_u32_e32 v92, s26, v197
	ds_read_b128 v[60:63], v72
	ds_read_b128 v[64:67], v72 offset:1024
	ds_read_b128 v[68:71], v72 offset:2048
	ds_read_b128 v[72:75], v72 offset:3072
	ds_read_b128 v[76:79], v92
	ds_read_b128 v[80:83], v92 offset:1024
	ds_read_b128 v[88:91], v92 offset:2048
	ds_read_b128 v[92:95], v92 offset:3072
	v_lshl_add_u64 v[210:211], s[10:11], 0, v[180:181]
	s_add_i32 m0, s40, 0xc000
	ds_read_b128 v[160:163], v201
	ds_read_b128 v[164:167], v201 offset:1024
	ds_read_b128 v[168:171], v201 offset:2048
	ds_read_b128 v[172:175], v201 offset:3072
	ds_read_b128 v[182:185], v201 offset:4096
	ds_read_b128 v[186:189], v201 offset:5120
	ds_read_b128 v[202:205], v201 offset:6144
	ds_read_b128 v[206:209], v201 offset:7168
	global_load_lds_dwordx4 v[210:211], off
	v_lshl_add_u64 v[210:211], s[10:11], 0, v[178:179]
	s_add_i32 m0, s40, 0xe000
	s_nop 0
	global_load_lds_dwordx4 v[210:211], off
	s_waitcnt vmcnt(8) lgkmcnt(0)
	s_barrier
	s_setprio 1
	v_mfma_f32_16x16x32_bf16 v[156:159], v[60:63], v[160:163], v[156:159]
	v_mfma_f32_16x16x32_bf16 v[152:155], v[68:71], v[160:163], v[152:155]
	v_mfma_f32_16x16x32_bf16 v[140:143], v[60:63], v[168:171], v[140:143]
	v_mfma_f32_16x16x32_bf16 v[136:139], v[68:71], v[168:171], v[136:139]
	v_mfma_f32_16x16x32_bf16 v[124:127], v[60:63], v[182:185], v[124:127]
	v_mfma_f32_16x16x32_bf16 v[120:123], v[68:71], v[182:185], v[120:123]
	v_mfma_f32_16x16x32_bf16 v[108:111], v[60:63], v[202:205], v[108:111]
	v_mfma_f32_16x16x32_bf16 v[104:107], v[68:71], v[202:205], v[104:107]
	v_mfma_f32_16x16x32_bf16 v[156:159], v[64:67], v[164:167], v[156:159]
	v_mfma_f32_16x16x32_bf16 v[152:155], v[72:75], v[164:167], v[152:155]
	v_mfma_f32_16x16x32_bf16 v[140:143], v[64:67], v[172:175], v[140:143]
	v_mfma_f32_16x16x32_bf16 v[136:139], v[72:75], v[172:175], v[136:139]
	v_mfma_f32_16x16x32_bf16 v[124:127], v[64:67], v[186:189], v[124:127]
	v_mfma_f32_16x16x32_bf16 v[120:123], v[72:75], v[186:189], v[120:123]
	v_mfma_f32_16x16x32_bf16 v[108:111], v[64:67], v[206:209], v[108:111]
	v_mfma_f32_16x16x32_bf16 v[104:107], v[72:75], v[206:209], v[104:107]
	s_setprio 0
	s_setprio 1
	v_mfma_f32_16x16x32_bf16 v[148:151], v[76:79], v[160:163], v[148:151]
	v_mfma_f32_16x16x32_bf16 v[144:147], v[88:91], v[160:163], v[144:147]
	v_mfma_f32_16x16x32_bf16 v[132:135], v[76:79], v[168:171], v[132:135]
	v_mfma_f32_16x16x32_bf16 v[128:131], v[88:91], v[168:171], v[128:131]
	v_mfma_f32_16x16x32_bf16 v[116:119], v[76:79], v[182:185], v[116:119]
	v_mfma_f32_16x16x32_bf16 v[112:115], v[88:91], v[182:185], v[112:115]
	v_mfma_f32_16x16x32_bf16 v[100:103], v[76:79], v[202:205], v[100:103]
	v_mfma_f32_16x16x32_bf16 v[96:99], v[88:91], v[202:205], v[96:99]
	v_mfma_f32_16x16x32_bf16 v[148:151], v[80:83], v[164:167], v[148:151]
	v_mfma_f32_16x16x32_bf16 v[144:147], v[92:95], v[164:167], v[144:147]
	v_mfma_f32_16x16x32_bf16 v[132:135], v[80:83], v[172:175], v[132:135]
	v_mfma_f32_16x16x32_bf16 v[128:131], v[92:95], v[172:175], v[128:131]
	v_mfma_f32_16x16x32_bf16 v[116:119], v[80:83], v[186:189], v[116:119]
	v_mfma_f32_16x16x32_bf16 v[112:115], v[92:95], v[186:189], v[112:115]
	v_mfma_f32_16x16x32_bf16 v[100:103], v[80:83], v[206:209], v[100:103]
	v_mfma_f32_16x16x32_bf16 v[96:99], v[92:95], v[206:209], v[96:99]
	s_setprio 0
	s_barrier
	s_add_i32 s10, s25, s23
	v_lshl_add_u64 v[210:211], s[50:51], 0, v[192:193]
	s_mov_b32 m0, s10
	ds_read_b128 v[160:163], v201 offset:16384
	ds_read_b128 v[164:167], v201 offset:17408
	ds_read_b128 v[168:171], v201 offset:18432
	ds_read_b128 v[172:175], v201 offset:19456
	ds_read_b128 v[182:185], v201 offset:20480
	ds_read_b128 v[186:189], v201 offset:21504
	ds_read_b128 v[202:205], v201 offset:22528
	ds_read_b128 v[206:209], v201 offset:23552
	global_load_lds_dwordx4 v[210:211], off
	s_add_i32 m0, s10, 0x2000
	s_add_u32 s10, s50, 0xb0000
	v_lshl_add_u64 v[212:213], s[50:51], 0, v[176:177]
	s_addc_u32 s11, s51, 0
	s_add_i32 s25, s26, s23
	global_load_lds_dwordx4 v[212:213], off
	v_lshl_add_u64 v[214:215], s[10:11], 0, v[192:193]
	s_mov_b32 m0, s25
	v_lshl_add_u64 v[216:217], s[52:53], 0, v[176:177]
	global_load_lds_dwordx4 v[214:215], off
	v_lshl_add_u64 v[214:215], s[10:11], 0, v[176:177]
	s_add_i32 m0, s25, 0x2000
	s_nop 0
	global_load_lds_dwordx4 v[214:215], off
	v_lshl_add_u64 v[214:215], s[52:53], 0, v[192:193]
	s_mov_b32 m0, s40
	s_nop 0
	global_load_lds_dwordx4 v[214:215], off
	s_mov_b32 m0, s54
	s_nop 0
	global_load_lds_dwordx4 v[216:217], off
	s_waitcnt vmcnt(8) lgkmcnt(0)
	s_barrier
; #define PG8_STAGE(bufoff, gbase, voff) do { _Pragma("unroll") for (int _i = 0; _i < 2; ++_i) \
;         __builtin_amdgcn_global_load_lds((const unsigned*)((const char*)(gbase) + (voff)[_i]), (PG8_LAS unsigned*)(lds + (bufoff) + ldsw + _i * 8192), 16, 0, 0); } while (0)
; #define PG8_LDA(dst, b, h) do { _Pragma("unroll") for (int m = 0; m < 4; ++m) _Pragma("unroll") for (int k = 0; k < 2; ++k) dst[m][k] = *(const PG8_LAS bf16x8*)(lds + PG8_SA(b, h) + aoff + m * 2048 + k * 1024); } while (0)
; #define PG8_LDB(dst, b, h) do { _Pragma("unroll") for (int n = 0; n < 2; ++n) _Pragma("unroll") for (int k = 0; k < 2; ++k) dst[n][k] = *(const PG8_LAS bf16x8*)(lds + PG8_SB(b, h) + boff + n * 2048 + k * 1024); } while (0)
; #define PG8_MMA(ai, bj, At, Bt) do { __builtin_amdgcn_s_setprio(1); _Pragma("unroll") for (int m = 0; m < 4; ++m) _Pragma("unroll") for (int n = 0; n < 2; ++n) _Pragma("unroll") for (int k = 0; k < 2; ++k) \
;         acc[ai][bj][m][n] = __builtin_amdgcn_mfma_f32_16x16x32_bf16(Bt[n][k], At[m][k], acc[ai][bj][m][n], 0, 0, 0); __builtin_amdgcn_s_setprio(0); } while (0)
; #define PG8_WAIT_V(n) asm volatile("s_waitcnt vmcnt(" #n ")" ::: "memory")
; #define PG8_WAIT_L(n) asm volatile("s_waitcnt lgkmcnt(" #n ")" ::: "memory")
; #define PG8_BAR __builtin_amdgcn_s_barrier()
; #define PG8_SCHED __builtin_amdgcn_sched_barrier(0)
; template <class Epi, class Sched, bool ALIGN_EPI = false, bool SP2 = false>
; __device__ __forceinline__ void gemm_phase(PG8_LAS unsigned char* lds, const Gemm g, const Sched& S, const Epi& E, const int tid) {
;     ...
;             PG8_WAIT_V(8); PG8_WAIT_L(0); PG8_BAR; PG8_MMA(1, 0, At, B0); PG8_MMA(1, 1, At, B1); PG8_BAR; PG8_SCHED;
;             PG8_LDB(B0, 1, 0); PG8_LDB(B1, 1, 1); PG8_SCHED; PG8_LDA(At, 1, 0); PG8_STAGE(PG8_SA(0, 1), a2 + hstepA, voffA);
;             PG8_WAIT_V(8); PG8_WAIT_L(0); PG8_BAR; PG8_MMA(0, 0, At, B0); PG8_MMA(0, 1, At, B1); PG8_BAR; PG8_SCHED;
	s_setprio 1
	v_mfma_f32_16x16x32_bf16 v[84:87], v[60:63], v[160:163], v[84:87]
	v_mfma_f32_16x16x32_bf16 v[56:59], v[68:71], v[160:163], v[56:59]
	v_mfma_f32_16x16x32_bf16 v[44:47], v[60:63], v[168:171], v[44:47]
	v_mfma_f32_16x16x32_bf16 v[40:43], v[68:71], v[168:171], v[40:43]
	v_mfma_f32_16x16x32_bf16 v[28:31], v[60:63], v[182:185], v[28:31]
	v_mfma_f32_16x16x32_bf16 v[24:27], v[68:71], v[182:185], v[24:27]
	v_mfma_f32_16x16x32_bf16 v[12:15], v[60:63], v[202:205], v[12:15]
	v_mfma_f32_16x16x32_bf16 v[8:11], v[68:71], v[202:205], v[8:11]
	v_mfma_f32_16x16x32_bf16 v[84:87], v[64:67], v[164:167], v[84:87]
	v_mfma_f32_16x16x32_bf16 v[56:59], v[72:75], v[164:167], v[56:59]
	v_mfma_f32_16x16x32_bf16 v[44:47], v[64:67], v[172:175], v[44:47]
	v_mfma_f32_16x16x32_bf16 v[40:43], v[72:75], v[172:175], v[40:43]
	v_mfma_f32_16x16x32_bf16 v[28:31], v[64:67], v[186:189], v[28:31]
	v_mfma_f32_16x16x32_bf16 v[24:27], v[72:75], v[186:189], v[24:27]
	v_mfma_f32_16x16x32_bf16 v[12:15], v[64:67], v[206:209], v[12:15]
	v_mfma_f32_16x16x32_bf16 v[8:11], v[72:75], v[206:209], v[8:11]
	s_setprio 0
	s_setprio 1
	v_mfma_f32_16x16x32_bf16 v[52:55], v[76:79], v[160:163], v[52:55]
	v_mfma_f32_16x16x32_bf16 v[48:51], v[88:91], v[160:163], v[48:51]
	v_mfma_f32_16x16x32_bf16 v[36:39], v[76:79], v[168:171], v[36:39]
	v_mfma_f32_16x16x32_bf16 v[32:35], v[88:91], v[168:171], v[32:35]
	v_mfma_f32_16x16x32_bf16 v[20:23], v[76:79], v[182:185], v[20:23]
	v_mfma_f32_16x16x32_bf16 v[16:19], v[88:91], v[182:185], v[16:19]
	v_mfma_f32_16x16x32_bf16 v[4:7], v[76:79], v[202:205], v[4:7]
	v_mfma_f32_16x16x32_bf16 v[0:3], v[88:91], v[202:205], v[0:3]
	v_mfma_f32_16x16x32_bf16 v[52:55], v[80:83], v[164:167], v[52:55]
	v_mfma_f32_16x16x32_bf16 v[48:51], v[92:95], v[164:167], v[48:51]
	v_mfma_f32_16x16x32_bf16 v[36:39], v[80:83], v[172:175], v[36:39]
	v_mfma_f32_16x16x32_bf16 v[32:35], v[92:95], v[172:175], v[32:35]
	v_mfma_f32_16x16x32_bf16 v[20:23], v[80:83], v[186:189], v[20:23]
	v_mfma_f32_16x16x32_bf16 v[16:19], v[92:95], v[186:189], v[16:19]
	v_mfma_f32_16x16x32_bf16 v[4:7], v[80:83], v[206:209], v[4:7]
	v_mfma_f32_16x16x32_bf16 v[0:3], v[92:95], v[206:209], v[0:3]
	s_setprio 0
	s_barrier
	s_add_i32 s25, 0, 0x18000
	s_add_i32 s26, 0, 0x1c000
	v_add_u32_e32 v72, s25, v197
	v_add_u32_e32 v92, s26, v197
	ds_read_b128 v[60:63], v72
	ds_read_b128 v[64:67], v72 offset:1024
	ds_read_b128 v[68:71], v72 offset:2048
	ds_read_b128 v[72:75], v72 offset:3072
	ds_read_b128 v[76:79], v92
	ds_read_b128 v[80:83], v92 offset:1024
	ds_read_b128 v[88:91], v92 offset:2048
	ds_read_b128 v[92:95], v92 offset:3072
	s_add_u32 s10, s52, 0xb0000
	s_addc_u32 s11, s53, 0
	s_mov_b32 m0, s55
	v_lshl_add_u64 v[218:219], s[10:11], 0, v[192:193]
	ds_read_b128 v[160:163], v201 offset:32768
	ds_read_b128 v[164:167], v201 offset:33792
	ds_read_b128 v[168:171], v201 offset:34816
	ds_read_b128 v[172:175], v201 offset:35840
	ds_read_b128 v[182:185], v201 offset:36864
	ds_read_b128 v[186:189], v201 offset:37888
	ds_read_b128 v[202:205], v201 offset:38912
	ds_read_b128 v[206:209], v201 offset:39936
	global_load_lds_dwordx4 v[218:219], off
	v_lshl_add_u64 v[218:219], s[10:11], 0, v[176:177]
	s_mov_b32 m0, s58
	s_nop 0
	global_load_lds_dwordx4 v[218:219], off
	s_waitcnt vmcnt(8) lgkmcnt(0)
	s_barrier
	s_setprio 1
	v_mfma_f32_16x16x32_bf16 v[156:159], v[60:63], v[160:163], v[156:159]
	v_mfma_f32_16x16x32_bf16 v[152:155], v[68:71], v[160:163], v[152:155]
	v_mfma_f32_16x16x32_bf16 v[140:143], v[60:63], v[168:171], v[140:143]
	v_mfma_f32_16x16x32_bf16 v[136:139], v[68:71], v[168:171], v[136:139]
	v_mfma_f32_16x16x32_bf16 v[124:127], v[60:63], v[182:185], v[124:127]
	v_mfma_f32_16x16x32_bf16 v[120:123], v[68:71], v[182:185], v[120:123]
	v_mfma_f32_16x16x32_bf16 v[108:111], v[60:63], v[202:205], v[108:111]
	v_mfma_f32_16x16x32_bf16 v[104:107], v[68:71], v[202:205], v[104:107]
	v_mfma_f32_16x16x32_bf16 v[156:159], v[64:67], v[164:167], v[156:159]
	v_mfma_f32_16x16x32_bf16 v[152:155], v[72:75], v[164:167], v[152:155]
	v_mfma_f32_16x16x32_bf16 v[140:143], v[64:67], v[172:175], v[140:143]
	v_mfma_f32_16x16x32_bf16 v[136:139], v[72:75], v[172:175], v[136:139]
	v_mfma_f32_16x16x32_bf16 v[124:127], v[64:67], v[186:189], v[124:127]
	v_mfma_f32_16x16x32_bf16 v[120:123], v[72:75], v[186:189], v[120:123]
	v_mfma_f32_16x16x32_bf16 v[108:111], v[64:67], v[206:209], v[108:111]
	v_mfma_f32_16x16x32_bf16 v[104:107], v[72:75], v[206:209], v[104:107]
	s_setprio 0
	s_setprio 1
	v_mfma_f32_16x16x32_bf16 v[148:151], v[76:79], v[160:163], v[148:151]
	v_mfma_f32_16x16x32_bf16 v[144:147], v[88:91], v[160:163], v[144:147]
	v_mfma_f32_16x16x32_bf16 v[132:135], v[76:79], v[168:171], v[132:135]
	v_mfma_f32_16x16x32_bf16 v[128:131], v[88:91], v[168:171], v[128:131]
	v_mfma_f32_16x16x32_bf16 v[116:119], v[76:79], v[182:185], v[116:119]
	v_mfma_f32_16x16x32_bf16 v[112:115], v[88:91], v[182:185], v[112:115]
	v_mfma_f32_16x16x32_bf16 v[100:103], v[76:79], v[202:205], v[100:103]
	v_mfma_f32_16x16x32_bf16 v[96:99], v[88:91], v[202:205], v[96:99]
	v_mfma_f32_16x16x32_bf16 v[148:151], v[80:83], v[164:167], v[148:151]
	v_mfma_f32_16x16x32_bf16 v[144:147], v[92:95], v[164:167], v[144:147]
	v_mfma_f32_16x16x32_bf16 v[132:135], v[80:83], v[172:175], v[132:135]
	v_mfma_f32_16x16x32_bf16 v[128:131], v[92:95], v[172:175], v[128:131]
	v_mfma_f32_16x16x32_bf16 v[116:119], v[80:83], v[186:189], v[116:119]
	v_mfma_f32_16x16x32_bf16 v[112:115], v[92:95], v[186:189], v[112:115]
	v_mfma_f32_16x16x32_bf16 v[100:103], v[80:83], v[206:209], v[100:103]
	v_mfma_f32_16x16x32_bf16 v[96:99], v[92:95], v[206:209], v[96:99]
	s_setprio 0
	s_barrier
; #define PG8_STAGE(bufoff, gbase, voff) do { _Pragma("unroll") for (int _i = 0; _i < 2; ++_i) \
;         __builtin_amdgcn_global_load_lds((const unsigned*)((const char*)(gbase) + (voff)[_i]), (PG8_LAS unsigned*)(lds + (bufoff) + ldsw + _i * 8192), 16, 0, 0); } while (0)
; #define PG8_LDA(dst, b, h) do { _Pragma("unroll") for (int m = 0; m < 4; ++m) _Pragma("unroll") for (int k = 0; k < 2; ++k) dst[m][k] = *(const PG8_LAS bf16x8*)(lds + PG8_SA(b, h) + aoff + m * 2048 + k * 1024); } while (0)
; #define PG8_MMA(ai, bj, At, Bt) do { __builtin_amdgcn_s_setprio(1); _Pragma("unroll") for (int m = 0; m < 4; ++m) _Pragma("unroll") for (int n = 0; n < 2; ++n) _Pragma("unroll") for (int k = 0; k < 2; ++k) \
;         acc[ai][bj][m][n] = __builtin_amdgcn_mfma_f32_16x16x32_bf16(Bt[n][k], At[m][k], acc[ai][bj][m][n], 0, 0, 0); __builtin_amdgcn_s_setprio(0); } while (0)
; #define PG8_WAIT_V(n) asm volatile("s_waitcnt vmcnt(" #n ")" ::: "memory")
; #define PG8_WAIT_L(n) asm volatile("s_waitcnt lgkmcnt(" #n ")" ::: "memory")
; #define PG8_BAR __builtin_amdgcn_s_barrier()
; #define PG8_SCHED __builtin_amdgcn_sched_barrier(0)
; template <class Epi, class Sched, bool ALIGN_EPI = false, bool SP2 = false>
; __device__ __forceinline__ void gemm_phase(PG8_LAS unsigned char* lds, const Gemm g, const Sched& S, const Epi& E, const int tid) {
;     ...
;             PG8_LDA(At, 1, 1); PG8_STAGE(PG8_SB(1, 0), b3, voffB); PG8_STAGE(PG8_SB(1, 1), b3 + hstepB, voffB); PG8_STAGE(PG8_SA(1, 0), a3, voffA);
;             PG8_WAIT_V(8); PG8_WAIT_L(0); PG8_BAR; PG8_MMA(1, 0, At, B0); PG8_MMA(1, 1, At, B1); PG8_BAR; PG8_SCHED;
;     ...
;         if constexpr (ALIGN_EPI) { if (wr == 0) PG8_BAR; }
	s_add_i32 s10, s25, s23
	v_lshl_add_u64 v[210:211], v[210:211], 0, s[60:61]
	s_mov_b32 m0, s10
	ds_read_b128 v[160:163], v201 offset:49152
	ds_read_b128 v[164:167], v201 offset:50176
	ds_read_b128 v[168:171], v201 offset:51200
	ds_read_b128 v[172:175], v201 offset:52224
	ds_read_b128 v[182:185], v201 offset:53248
	ds_read_b128 v[186:189], v201 offset:54272
	ds_read_b128 v[202:205], v201 offset:55296
	ds_read_b128 v[206:209], v201 offset:56320
	global_load_lds_dwordx4 v[210:211], off
	s_add_i32 m0, s10, 0x2000
	s_add_u32 s10, s50, 0xb0080
	v_lshl_add_u64 v[210:211], v[212:213], 0, s[60:61]
	s_addc_u32 s11, s51, 0
	s_add_i32 s25, s26, s23
	global_load_lds_dwordx4 v[210:211], off
	v_lshl_add_u64 v[210:211], s[10:11], 0, v[192:193]
	s_mov_b32 m0, s25
	s_nop 0
	global_load_lds_dwordx4 v[210:211], off
	v_lshl_add_u64 v[210:211], s[10:11], 0, v[176:177]
	s_add_i32 m0, s25, 0x2000
	s_nop 0
	global_load_lds_dwordx4 v[210:211], off
	v_lshl_add_u64 v[210:211], v[214:215], 0, s[60:61]
	s_mov_b32 m0, s79
	s_nop 0
	global_load_lds_dwordx4 v[210:211], off
	v_lshl_add_u64 v[210:211], v[216:217], 0, s[60:61]
	s_mov_b32 m0, s80
	s_nop 0
	global_load_lds_dwordx4 v[210:211], off
	s_waitcnt vmcnt(8) lgkmcnt(0)
	s_barrier
	s_setprio 1
	v_mfma_f32_16x16x32_bf16 v[84:87], v[60:63], v[160:163], v[84:87]
	v_mfma_f32_16x16x32_bf16 v[56:59], v[68:71], v[160:163], v[56:59]
	v_mfma_f32_16x16x32_bf16 v[44:47], v[60:63], v[168:171], v[44:47]
	v_mfma_f32_16x16x32_bf16 v[40:43], v[68:71], v[168:171], v[40:43]
	v_mfma_f32_16x16x32_bf16 v[28:31], v[60:63], v[182:185], v[28:31]
	v_mfma_f32_16x16x32_bf16 v[24:27], v[68:71], v[182:185], v[24:27]
	v_mfma_f32_16x16x32_bf16 v[12:15], v[60:63], v[202:205], v[12:15]
	v_mfma_f32_16x16x32_bf16 v[8:11], v[68:71], v[202:205], v[8:11]
	v_mfma_f32_16x16x32_bf16 v[84:87], v[64:67], v[164:167], v[84:87]
	v_mfma_f32_16x16x32_bf16 v[56:59], v[72:75], v[164:167], v[56:59]
	v_mfma_f32_16x16x32_bf16 v[44:47], v[64:67], v[172:175], v[44:47]
	v_mfma_f32_16x16x32_bf16 v[40:43], v[72:75], v[172:175], v[40:43]
	v_mfma_f32_16x16x32_bf16 v[28:31], v[64:67], v[186:189], v[28:31]
	v_mfma_f32_16x16x32_bf16 v[24:27], v[72:75], v[186:189], v[24:27]
	v_mfma_f32_16x16x32_bf16 v[12:15], v[64:67], v[206:209], v[12:15]
	v_mfma_f32_16x16x32_bf16 v[8:11], v[72:75], v[206:209], v[8:11]
	s_setprio 0
	s_setprio 1
	v_mfma_f32_16x16x32_bf16 v[52:55], v[76:79], v[160:163], v[52:55]
	v_mfma_f32_16x16x32_bf16 v[48:51], v[88:91], v[160:163], v[48:51]
	v_mfma_f32_16x16x32_bf16 v[36:39], v[76:79], v[168:171], v[36:39]
	v_mfma_f32_16x16x32_bf16 v[32:35], v[88:91], v[168:171], v[32:35]
	v_mfma_f32_16x16x32_bf16 v[20:23], v[76:79], v[182:185], v[20:23]
	v_mfma_f32_16x16x32_bf16 v[16:19], v[88:91], v[182:185], v[16:19]
	v_mfma_f32_16x16x32_bf16 v[4:7], v[76:79], v[202:205], v[4:7]
	v_mfma_f32_16x16x32_bf16 v[0:3], v[88:91], v[202:205], v[0:3]
	v_mfma_f32_16x16x32_bf16 v[52:55], v[80:83], v[164:167], v[52:55]
	v_mfma_f32_16x16x32_bf16 v[48:51], v[92:95], v[164:167], v[48:51]
	v_mfma_f32_16x16x32_bf16 v[36:39], v[80:83], v[172:175], v[36:39]
	v_mfma_f32_16x16x32_bf16 v[32:35], v[92:95], v[172:175], v[32:35]
	v_mfma_f32_16x16x32_bf16 v[20:23], v[80:83], v[186:189], v[20:23]
	v_mfma_f32_16x16x32_bf16 v[16:19], v[92:95], v[186:189], v[16:19]
	v_mfma_f32_16x16x32_bf16 v[4:7], v[80:83], v[206:209], v[4:7]
	v_mfma_f32_16x16x32_bf16 v[0:3], v[92:95], v[206:209], v[0:3]
	s_setprio 0
	s_barrier
	s_add_i32 s24, s24, 2
	s_add_u32 s20, s20, 0x100
	s_addc_u32 s21, s21, 0
	s_cmp_gt_u32 s24, 41
	s_mov_b64 s[10:11], s[48:49]
	s_cbranch_scc0 .LBB0_347
	s_and_b64 vcc, exec, s[42:43]
	s_cbranch_vccz .LBB0_350
	s_barrier
